# v23 + peeled first K-iteration per GEMM unit (srcC=0 for each accumulator's first MFMA), 128 v_mov zeroing per unit removed in in-proj/FF1/FF2
# baseline (speedup 1.0000x reference)
; #define PG8_STAGE(bufoff, gbase, voff) do { _Pragma("unroll") for (int _i = 0; _i < 2; ++_i) \
;         __builtin_amdgcn_global_load_lds((const unsigned*)((const char*)(gbase) + (voff)[_i]), (PG8_LAS unsigned*)(lds + (bufoff) + ldsw + _i * 8192), 16, 0, 0); } while (0)
; #define PG8_LDA(dst, b, h) do { _Pragma("unroll") for (int m = 0; m < 4; ++m) _Pragma("unroll") for (int k = 0; k < 2; ++k) dst[m][k] = *(const PG8_LAS bf16x8*)(lds + PG8_SA(b, h) + aoff + m * 2048 + k * 1024); } while (0)
; #define PG8_LDB(dst, b, h) do { _Pragma("unroll") for (int n = 0; n < 2; ++n) _Pragma("unroll") for (int k = 0; k < 2; ++k) dst[n][k] = *(const PG8_LAS bf16x8*)(lds + PG8_SB(b, h) + boff + n * 2048 + k * 1024); } while (0)
; #define PG8_WAIT_V(n) asm volatile("s_waitcnt vmcnt(" #n ")" ::: "memory")
; template <class Epi, class Sched, bool ALIGN_EPI = false, bool SP2 = false>
; __device__ __forceinline__ void gemm_phase(PG8_LAS unsigned char* lds, const Gemm g, const Sched& S, const Epi& E) {
;     ...
;             if constexpr (SP2) {
;             PG8_LDB(B0, 0, 0); PG8_LDB(B1, 0, 1); PG8_SCHED; PG8_LDA(At, 0, 0); PG8_STAGE(PG8_SA(1, 1), a1 + hstep, voffA);
;             PG8_WAIT_V(8); PG8_WAIT_L(0); PG8_BAR; PG8_MMA(0, 0, At, B0); PG8_MMA(0, 1, At, B1); PG8_BAR; PG8_SCHED;
;             PG8_LDA(At, 0, 1); PG8_STAGE(PG8_SB(0, 0), b2, voffB); PG8_STAGE(PG8_SB(0, 1), b2 + hstep, voffB); PG8_STAGE(PG8_SA(0, 0), a2, voffA);
;             PG8_WAIT_V(8); PG8_WAIT_L(0); PG8_BAR; PG8_MMA(1, 0, At, B0); PG8_MMA(1, 1, At, B1); PG8_BAR; PG8_SCHED;
;             PG8_LDB(B0, 1, 0); PG8_LDB(B1, 1, 1); PG8_SCHED; PG8_LDA(At, 1, 0); PG8_STAGE(PG8_SA(0, 1), a2 + hstep, voffA);
;             PG8_WAIT_V(8); PG8_WAIT_L(0); PG8_BAR; PG8_MMA(0, 0, At, B0); PG8_MMA(0, 1, At, B1); PG8_BAR; PG8_SCHED;
;             PG8_LDA(At, 1, 1); PG8_STAGE(PG8_SB(1, 0), b3, voffB); PG8_STAGE(PG8_SB(1, 1), b3 + hstep, voffB); PG8_STAGE(PG8_SA(1, 0), a3, voffA);
;             PG8_WAIT_V(8); PG8_WAIT_L(0); PG8_BAR; PG8_MMA(1, 0, At, B0); PG8_MMA(1, 1, At, B1); PG8_BAR; PG8_SCHED;
;     ...
; #pragma unroll
;         for (int a = 0; a < 2; ++a)
; #pragma unroll
;             for (int b = 0; b < 2; ++b)
; #pragma unroll
;                 for (int m = 0; m < 4; ++m)
; #pragma unroll
;                     for (int n = 0; n < 2; ++n) acc[a][b][m][n] = (f32x4){0.f, 0.f, 0.f, 0.f};
;         cur = nxt; cA = nA; cB = nB; ++ui;
.LBB0_348:
	s_add_u32 s88, s88, 0x100080
	s_addc_u32 s89, s89, 0
	s_add_u32 s9, s90, 0x100
	s_addc_u32 s21, s91, 0
	s_mov_b32 s23, -2
	s_cmp_lt_u32 s27, 0x1000
	s_cbranch_scc0 .Lip_h1first
	ds_read_b128 v[150:153], v169
	ds_read_b128 v[154:157], v169 offset:1024
	ds_read_b128 v[158:161], v169 offset:2048
	ds_read_b128 v[162:165], v169 offset:3072
	ds_read_b128 v[174:177], v170
	ds_read_b128 v[178:181], v170 offset:1024
	ds_read_b128 v[182:185], v170 offset:2048
	ds_read_b128 v[186:189], v170 offset:3072
	s_add_u32 s0, s88, 0xfff00080
	s_addc_u32 s1, s89, -1
	s_cmp_eq_u32 s23, 60
	s_cselect_b32 s93, s51, s1
	s_cselect_b32 s92, s50, s0
	s_cselect_b32 s91, s53, s21
	s_cselect_b32 s90, s52, s9
	ds_read_b128 v[190:193], v171
	ds_read_b128 v[196:199], v171 offset:1024
	ds_read_b128 v[200:203], v171 offset:2048
	ds_read_b128 v[204:207], v171 offset:3072
	ds_read_b128 v[208:211], v171 offset:4096
	ds_read_b128 v[212:215], v171 offset:5120
	ds_read_b128 v[220:223], v171 offset:6144
	ds_read_b128 v[224:227], v171 offset:7168
	s_add_u32 s0, s88, 0xfff00000
	s_addc_u32 s1, s89, -1
	s_add_i32 m0, s27, 0x8000
	s_nop 0
	global_load_lds_dwordx4 v134, s[0:1]
	s_add_i32 m0, s27, 0xa000
	s_nop 0
	global_load_lds_dwordx4 v138, s[0:1]
	s_add_i32 m0, s27, 0xc000
	s_nop 0
	global_load_lds_dwordx4 v134, s[88:89]
	s_add_i32 m0, s27, 0xe000
	s_nop 0
	global_load_lds_dwordx4 v138, s[88:89]
	s_waitcnt lgkmcnt(0)
	s_setprio 1
	v_mfma_f32_16x16x32_bf16 v[38:41], v[150:153], v[190:193], 0
	v_mfma_f32_16x16x32_bf16 v[30:33], v[158:161], v[190:193], 0
	v_mfma_f32_16x16x32_bf16 v[130:133], v[150:153], v[200:203], 0
	v_mfma_f32_16x16x32_bf16 v[126:129], v[158:161], v[200:203], 0
	v_mfma_f32_16x16x32_bf16 v[114:117], v[150:153], v[208:211], 0
	v_mfma_f32_16x16x32_bf16 v[110:113], v[158:161], v[208:211], 0
	v_mfma_f32_16x16x32_bf16 v[98:101], v[150:153], v[220:223], 0
	v_mfma_f32_16x16x32_bf16 v[94:97], v[158:161], v[220:223], 0
	v_mfma_f32_16x16x32_bf16 v[38:41], v[154:157], v[196:199], v[38:41]
	v_mfma_f32_16x16x32_bf16 v[30:33], v[162:165], v[196:199], v[30:33]
	v_mfma_f32_16x16x32_bf16 v[130:133], v[154:157], v[204:207], v[130:133]
	v_mfma_f32_16x16x32_bf16 v[126:129], v[162:165], v[204:207], v[126:129]
	v_mfma_f32_16x16x32_bf16 v[114:117], v[154:157], v[212:215], v[114:117]
	v_mfma_f32_16x16x32_bf16 v[110:113], v[162:165], v[212:215], v[110:113]
	v_mfma_f32_16x16x32_bf16 v[98:101], v[154:157], v[224:227], v[98:101]
	v_mfma_f32_16x16x32_bf16 v[94:97], v[162:165], v[224:227], v[94:97]
	v_mfma_f32_16x16x32_bf16 v[50:53], v[174:177], v[190:193], 0
	v_mfma_f32_16x16x32_bf16 v[46:49], v[182:185], v[190:193], 0
	v_mfma_f32_16x16x32_bf16 v[122:125], v[174:177], v[200:203], 0
	v_mfma_f32_16x16x32_bf16 v[118:121], v[182:185], v[200:203], 0
	v_mfma_f32_16x16x32_bf16 v[106:109], v[174:177], v[208:211], 0
	v_mfma_f32_16x16x32_bf16 v[102:105], v[182:185], v[208:211], 0
	v_mfma_f32_16x16x32_bf16 v[90:93], v[174:177], v[220:223], 0
	v_mfma_f32_16x16x32_bf16 v[86:89], v[182:185], v[220:223], 0
	v_mfma_f32_16x16x32_bf16 v[50:53], v[178:181], v[196:199], v[50:53]
	v_mfma_f32_16x16x32_bf16 v[46:49], v[186:189], v[196:199], v[46:49]
	v_mfma_f32_16x16x32_bf16 v[122:125], v[178:181], v[204:207], v[122:125]
	v_mfma_f32_16x16x32_bf16 v[118:121], v[186:189], v[204:207], v[118:121]
	v_mfma_f32_16x16x32_bf16 v[106:109], v[178:181], v[212:215], v[106:109]
	v_mfma_f32_16x16x32_bf16 v[102:105], v[186:189], v[212:215], v[102:105]
	v_mfma_f32_16x16x32_bf16 v[90:93], v[178:181], v[224:227], v[90:93]
	v_mfma_f32_16x16x32_bf16 v[86:89], v[186:189], v[224:227], v[86:89]
	s_setprio 0
	s_waitcnt vmcnt(8)
	s_barrier
	ds_read_b128 v[190:193], v171 offset:16384
	ds_read_b128 v[196:199], v171 offset:17408
	ds_read_b128 v[200:203], v171 offset:18432
	ds_read_b128 v[204:207], v171 offset:19456
	ds_read_b128 v[208:211], v171 offset:20480
	ds_read_b128 v[212:215], v171 offset:21504
	ds_read_b128 v[220:223], v171 offset:22528
	ds_read_b128 v[224:227], v171 offset:23552
	s_add_u32 vcc_lo, s90, 0x100000
	s_addc_u32 vcc_hi, s91, 0
	s_add_i32 m0, s27, 0x10000
	s_nop 0
	global_load_lds_dwordx4 v136, s[90:91]
	s_add_i32 m0, s27, 0x12000
	s_nop 0
	global_load_lds_dwordx4 v140, s[90:91]
	s_add_i32 m0, s27, 0x14000
	s_nop 0
	global_load_lds_dwordx4 v136, vcc
	s_add_i32 m0, s27, 0x16000
	s_nop 0
	global_load_lds_dwordx4 v140, vcc
	s_waitcnt lgkmcnt(0)
	s_setprio 1
	v_mfma_f32_16x16x32_bf16 v[82:85], v[150:153], v[190:193], 0
	v_mfma_f32_16x16x32_bf16 v[78:81], v[158:161], v[190:193], 0
	v_mfma_f32_16x16x32_bf16 v[66:69], v[150:153], v[200:203], 0
	v_mfma_f32_16x16x32_bf16 v[62:65], v[158:161], v[200:203], 0
	v_mfma_f32_16x16x32_bf16 v[42:45], v[150:153], v[208:211], 0
	v_mfma_f32_16x16x32_bf16 v[34:37], v[158:161], v[208:211], 0
	v_mfma_f32_16x16x32_bf16 v[18:21], v[150:153], v[220:223], 0
	v_mfma_f32_16x16x32_bf16 v[14:17], v[158:161], v[220:223], 0
	v_mfma_f32_16x16x32_bf16 v[82:85], v[154:157], v[196:199], v[82:85]
	v_mfma_f32_16x16x32_bf16 v[78:81], v[162:165], v[196:199], v[78:81]
	v_mfma_f32_16x16x32_bf16 v[66:69], v[154:157], v[204:207], v[66:69]
	v_mfma_f32_16x16x32_bf16 v[62:65], v[162:165], v[204:207], v[62:65]
	v_mfma_f32_16x16x32_bf16 v[42:45], v[154:157], v[212:215], v[42:45]
	v_mfma_f32_16x16x32_bf16 v[34:37], v[162:165], v[212:215], v[34:37]
	v_mfma_f32_16x16x32_bf16 v[18:21], v[154:157], v[224:227], v[18:21]
	v_mfma_f32_16x16x32_bf16 v[14:17], v[162:165], v[224:227], v[14:17]
	v_mfma_f32_16x16x32_bf16 v[74:77], v[174:177], v[190:193], 0
	v_mfma_f32_16x16x32_bf16 v[70:73], v[182:185], v[190:193], 0
	v_mfma_f32_16x16x32_bf16 v[58:61], v[174:177], v[200:203], 0
	v_mfma_f32_16x16x32_bf16 v[54:57], v[182:185], v[200:203], 0
	v_mfma_f32_16x16x32_bf16 v[26:29], v[174:177], v[208:211], 0
	v_mfma_f32_16x16x32_bf16 v[22:25], v[182:185], v[208:211], 0
	v_mfma_f32_16x16x32_bf16 v[10:13], v[174:177], v[220:223], 0
	v_mfma_f32_16x16x32_bf16 v[4:7], v[182:185], v[220:223], 0
	v_mfma_f32_16x16x32_bf16 v[74:77], v[178:181], v[196:199], v[74:77]
	v_mfma_f32_16x16x32_bf16 v[70:73], v[186:189], v[196:199], v[70:73]
	v_mfma_f32_16x16x32_bf16 v[58:61], v[178:181], v[204:207], v[58:61]
	v_mfma_f32_16x16x32_bf16 v[54:57], v[186:189], v[204:207], v[54:57]
	v_mfma_f32_16x16x32_bf16 v[26:29], v[178:181], v[212:215], v[26:29]
	v_mfma_f32_16x16x32_bf16 v[22:25], v[186:189], v[212:215], v[22:25]
	v_mfma_f32_16x16x32_bf16 v[10:13], v[178:181], v[224:227], v[10:13]
	v_mfma_f32_16x16x32_bf16 v[4:7], v[186:189], v[224:227], v[4:7]
	s_setprio 0
	s_waitcnt vmcnt(6)
	s_barrier
; #define PG8_STAGE(bufoff, gbase, voff) do { _Pragma("unroll") for (int _i = 0; _i < 2; ++_i) \
;         __builtin_amdgcn_global_load_lds((const unsigned*)((const char*)(gbase) + (voff)[_i]), (PG8_LAS unsigned*)(lds + (bufoff) + ldsw + _i * 8192), 16, 0, 0); } while (0)
; #define PG8_LDA(dst, b, h) do { _Pragma("unroll") for (int m = 0; m < 4; ++m) _Pragma("unroll") for (int k = 0; k < 2; ++k) dst[m][k] = *(const PG8_LAS bf16x8*)(lds + PG8_SA(b, h) + aoff + m * 2048 + k * 1024); } while (0)
; #define PG8_LDB(dst, b, h) do { _Pragma("unroll") for (int n = 0; n < 2; ++n) _Pragma("unroll") for (int k = 0; k < 2; ++k) dst[n][k] = *(const PG8_LAS bf16x8*)(lds + PG8_SB(b, h) + boff + n * 2048 + k * 1024); } while (0)
; #define PG8_MMA(ai, bj, At, Bt) do { __builtin_amdgcn_s_setprio(1); _Pragma("unroll") for (int m = 0; m < 4; ++m) _Pragma("unroll") for (int n = 0; n < 2; ++n) _Pragma("unroll") for (int k = 0; k < 2; ++k) \
;         acc[ai][bj][m][n] = __builtin_amdgcn_mfma_f32_16x16x32_bf16(Bt[n][k], At[m][k], acc[ai][bj][m][n], 0, 0, 0); __builtin_amdgcn_s_setprio(0); } while (0)
; #define PG8_BAR __builtin_amdgcn_s_barrier()
; template <class Epi, class Sched, bool ALIGN_EPI = false, bool SP2 = false>
; __device__ __forceinline__ void gemm_phase(PG8_LAS unsigned char* lds, const Gemm g, const Sched& S, const Epi& E) {
;     ...
;             if constexpr (SP2) {
;             PG8_LDB(B0, 0, 0); PG8_LDB(B1, 0, 1); PG8_SCHED; PG8_LDA(At, 0, 0); PG8_STAGE(PG8_SA(1, 1), a1 + hstep, voffA);
;             PG8_WAIT_V(8); PG8_WAIT_L(0); PG8_BAR; PG8_MMA(0, 0, At, B0); PG8_MMA(0, 1, At, B1); PG8_BAR; PG8_SCHED;
;             PG8_LDA(At, 0, 1); PG8_STAGE(PG8_SB(0, 0), b2, voffB); PG8_STAGE(PG8_SB(0, 1), b2 + hstep, voffB); PG8_STAGE(PG8_SA(0, 0), a2, voffA);
;             PG8_WAIT_V(8); PG8_WAIT_L(0); PG8_BAR; PG8_MMA(1, 0, At, B0); PG8_MMA(1, 1, At, B1); PG8_BAR; PG8_SCHED;
;             PG8_LDB(B0, 1, 0); PG8_LDB(B1, 1, 1); PG8_SCHED; PG8_LDA(At, 1, 0); PG8_STAGE(PG8_SA(0, 1), a2 + hstep, voffA);
;             PG8_WAIT_V(8); PG8_WAIT_L(0); PG8_BAR; PG8_MMA(0, 0, At, B0); PG8_MMA(0, 1, At, B1); PG8_BAR; PG8_SCHED;
;             PG8_LDA(At, 1, 1); PG8_STAGE(PG8_SB(1, 0), b3, voffB); PG8_STAGE(PG8_SB(1, 1), b3 + hstep, voffB); PG8_STAGE(PG8_SA(1, 0), a3, voffA);
;             PG8_WAIT_V(8); PG8_WAIT_L(0); PG8_BAR; PG8_MMA(1, 0, At, B0); PG8_MMA(1, 1, At, B1); PG8_BAR; PG8_SCHED;
	s_add_i32 s0, 0, 0x18000
	v_add_u32_e32 v3, s0, v167
	s_add_i32 s1, 0, 0x1c000
	ds_read_b128 v[150:153], v3
	ds_read_b128 v[154:157], v3 offset:1024
	ds_read_b128 v[158:161], v3 offset:2048
	ds_read_b128 v[162:165], v3 offset:3072
	v_add_u32_e32 v3, s1, v167
	ds_read_b128 v[174:177], v3
	ds_read_b128 v[178:181], v3 offset:1024
	ds_read_b128 v[182:185], v3 offset:2048
	ds_read_b128 v[186:189], v3 offset:3072
	ds_read_b128 v[190:193], v171 offset:32768
	ds_read_b128 v[196:199], v171 offset:33792
	ds_read_b128 v[200:203], v171 offset:34816
	ds_read_b128 v[204:207], v171 offset:35840
	ds_read_b128 v[208:211], v171 offset:36864
	ds_read_b128 v[212:215], v171 offset:37888
	ds_read_b128 v[220:223], v171 offset:38912
	ds_read_b128 v[224:227], v171 offset:39936
	s_add_u32 vcc_lo, s92, 0x100000
	s_addc_u32 vcc_hi, s93, 0
	s_mov_b32 m0, s27
	s_nop 0
	global_load_lds_dwordx4 v134, s[92:93]
	s_add_i32 m0, s27, 0x2000
	s_nop 0
	global_load_lds_dwordx4 v138, s[92:93]
	s_add_i32 m0, s27, 0x4000
	s_nop 0
	global_load_lds_dwordx4 v134, vcc
	s_add_i32 m0, s27, 0x6000
	s_nop 0
	global_load_lds_dwordx4 v138, vcc
	s_waitcnt lgkmcnt(0)
	s_setprio 1
	v_mfma_f32_16x16x32_bf16 v[38:41], v[150:153], v[190:193], v[38:41]
	v_mfma_f32_16x16x32_bf16 v[30:33], v[158:161], v[190:193], v[30:33]
	v_mfma_f32_16x16x32_bf16 v[130:133], v[150:153], v[200:203], v[130:133]
	v_mfma_f32_16x16x32_bf16 v[126:129], v[158:161], v[200:203], v[126:129]
	v_mfma_f32_16x16x32_bf16 v[114:117], v[150:153], v[208:211], v[114:117]
	v_mfma_f32_16x16x32_bf16 v[110:113], v[158:161], v[208:211], v[110:113]
	v_mfma_f32_16x16x32_bf16 v[98:101], v[150:153], v[220:223], v[98:101]
	v_mfma_f32_16x16x32_bf16 v[94:97], v[158:161], v[220:223], v[94:97]
	v_mfma_f32_16x16x32_bf16 v[38:41], v[154:157], v[196:199], v[38:41]
	v_mfma_f32_16x16x32_bf16 v[30:33], v[162:165], v[196:199], v[30:33]
	v_mfma_f32_16x16x32_bf16 v[130:133], v[154:157], v[204:207], v[130:133]
	v_mfma_f32_16x16x32_bf16 v[126:129], v[162:165], v[204:207], v[126:129]
	v_mfma_f32_16x16x32_bf16 v[114:117], v[154:157], v[212:215], v[114:117]
	v_mfma_f32_16x16x32_bf16 v[110:113], v[162:165], v[212:215], v[110:113]
	v_mfma_f32_16x16x32_bf16 v[98:101], v[154:157], v[224:227], v[98:101]
	v_mfma_f32_16x16x32_bf16 v[94:97], v[162:165], v[224:227], v[94:97]
	v_mfma_f32_16x16x32_bf16 v[50:53], v[174:177], v[190:193], v[50:53]
	v_mfma_f32_16x16x32_bf16 v[46:49], v[182:185], v[190:193], v[46:49]
	v_mfma_f32_16x16x32_bf16 v[122:125], v[174:177], v[200:203], v[122:125]
	v_mfma_f32_16x16x32_bf16 v[118:121], v[182:185], v[200:203], v[118:121]
	v_mfma_f32_16x16x32_bf16 v[106:109], v[174:177], v[208:211], v[106:109]
	v_mfma_f32_16x16x32_bf16 v[102:105], v[182:185], v[208:211], v[102:105]
	v_mfma_f32_16x16x32_bf16 v[90:93], v[174:177], v[220:223], v[90:93]
	v_mfma_f32_16x16x32_bf16 v[86:89], v[182:185], v[220:223], v[86:89]
	v_mfma_f32_16x16x32_bf16 v[50:53], v[178:181], v[196:199], v[50:53]
	v_mfma_f32_16x16x32_bf16 v[46:49], v[186:189], v[196:199], v[46:49]
	v_mfma_f32_16x16x32_bf16 v[122:125], v[178:181], v[204:207], v[122:125]
	v_mfma_f32_16x16x32_bf16 v[118:121], v[186:189], v[204:207], v[118:121]
	v_mfma_f32_16x16x32_bf16 v[106:109], v[178:181], v[212:215], v[106:109]
	v_mfma_f32_16x16x32_bf16 v[102:105], v[186:189], v[212:215], v[102:105]
	v_mfma_f32_16x16x32_bf16 v[90:93], v[178:181], v[224:227], v[90:93]
	v_mfma_f32_16x16x32_bf16 v[86:89], v[186:189], v[224:227], v[86:89]
	s_setprio 0
	s_waitcnt vmcnt(8)
	s_barrier
	ds_read_b128 v[190:193], v171 offset:49152
	ds_read_b128 v[196:199], v171 offset:50176
	ds_read_b128 v[200:203], v171 offset:51200
	ds_read_b128 v[204:207], v171 offset:52224
	ds_read_b128 v[208:211], v171 offset:53248
	ds_read_b128 v[212:215], v171 offset:54272
	ds_read_b128 v[220:223], v171 offset:55296
	ds_read_b128 v[224:227], v171 offset:56320
	s_add_u32 s0, s90, 0x80
	s_addc_u32 s1, s91, 0
	s_add_u32 vcc_lo, s0, 0x100000
	s_addc_u32 vcc_hi, s1, 0
	s_add_i32 m0, s27, 0x18000
	s_nop 0
	global_load_lds_dwordx4 v136, s[0:1]
	s_add_i32 m0, s27, 0x1a000
	s_nop 0
	global_load_lds_dwordx4 v140, s[0:1]
	s_add_i32 m0, s27, 0x1c000
	s_nop 0
	global_load_lds_dwordx4 v136, vcc
	s_add_i32 m0, s27, 0x1e000
	s_nop 0
	global_load_lds_dwordx4 v140, vcc
	s_waitcnt lgkmcnt(0)
	s_setprio 1
	v_mfma_f32_16x16x32_bf16 v[82:85], v[150:153], v[190:193], v[82:85]
	v_mfma_f32_16x16x32_bf16 v[78:81], v[158:161], v[190:193], v[78:81]
	v_mfma_f32_16x16x32_bf16 v[66:69], v[150:153], v[200:203], v[66:69]
	v_mfma_f32_16x16x32_bf16 v[62:65], v[158:161], v[200:203], v[62:65]
	v_mfma_f32_16x16x32_bf16 v[42:45], v[150:153], v[208:211], v[42:45]
	v_mfma_f32_16x16x32_bf16 v[34:37], v[158:161], v[208:211], v[34:37]
	v_mfma_f32_16x16x32_bf16 v[18:21], v[150:153], v[220:223], v[18:21]
	v_mfma_f32_16x16x32_bf16 v[14:17], v[158:161], v[220:223], v[14:17]
	v_mfma_f32_16x16x32_bf16 v[82:85], v[154:157], v[196:199], v[82:85]
	v_mfma_f32_16x16x32_bf16 v[78:81], v[162:165], v[196:199], v[78:81]
	v_mfma_f32_16x16x32_bf16 v[66:69], v[154:157], v[204:207], v[66:69]
	v_mfma_f32_16x16x32_bf16 v[62:65], v[162:165], v[204:207], v[62:65]
	v_mfma_f32_16x16x32_bf16 v[42:45], v[154:157], v[212:215], v[42:45]
	v_mfma_f32_16x16x32_bf16 v[34:37], v[162:165], v[212:215], v[34:37]
	v_mfma_f32_16x16x32_bf16 v[18:21], v[154:157], v[224:227], v[18:21]
	v_mfma_f32_16x16x32_bf16 v[14:17], v[162:165], v[224:227], v[14:17]
	v_mfma_f32_16x16x32_bf16 v[74:77], v[174:177], v[190:193], v[74:77]
	v_mfma_f32_16x16x32_bf16 v[70:73], v[182:185], v[190:193], v[70:73]
	v_mfma_f32_16x16x32_bf16 v[58:61], v[174:177], v[200:203], v[58:61]
	v_mfma_f32_16x16x32_bf16 v[54:57], v[182:185], v[200:203], v[54:57]
	v_mfma_f32_16x16x32_bf16 v[26:29], v[174:177], v[208:211], v[26:29]
	v_mfma_f32_16x16x32_bf16 v[22:25], v[182:185], v[208:211], v[22:25]
	v_mfma_f32_16x16x32_bf16 v[8:11], v[174:177], v[220:223], v[10:13]
	v_mfma_f32_16x16x32_bf16 v[4:7], v[182:185], v[220:223], v[4:7]
	v_mfma_f32_16x16x32_bf16 v[74:77], v[178:181], v[196:199], v[74:77]
	v_mfma_f32_16x16x32_bf16 v[70:73], v[186:189], v[196:199], v[70:73]
	v_mfma_f32_16x16x32_bf16 v[58:61], v[178:181], v[204:207], v[58:61]
	v_mfma_f32_16x16x32_bf16 v[54:57], v[186:189], v[204:207], v[54:57]
	v_mfma_f32_16x16x32_bf16 v[26:29], v[178:181], v[212:215], v[26:29]
	v_mfma_f32_16x16x32_bf16 v[22:25], v[186:189], v[212:215], v[22:25]
	v_mfma_f32_16x16x32_bf16 v[10:13], v[178:181], v[224:227], v[8:11]
	v_mfma_f32_16x16x32_bf16 v[6:9], v[186:189], v[224:227], v[4:7]
	s_setprio 0
	s_waitcnt vmcnt(6)
	s_barrier
	s_add_i32 s23, s23, 2
	s_add_u32 s88, s88, 0x100
	s_addc_u32 s89, s89, 0
	s_add_u32 s9, s9, 0x100
	s_addc_u32 s21, s21, 0
	s_cmp_gt_u32 s23, 61

; #define PG8_STAGE(bufoff, gbase, voff) do { _Pragma("unroll") for (int _i = 0; _i < 2; ++_i) \
;         __builtin_amdgcn_global_load_lds((const unsigned*)((const char*)(gbase) + (voff)[_i]), (PG8_LAS unsigned*)(lds + (bufoff) + ldsw + _i * 8192), 16, 0, 0); } while (0)
; #define PG8_LDA(dst, b, h) do { _Pragma("unroll") for (int m = 0; m < 4; ++m) _Pragma("unroll") for (int k = 0; k < 2; ++k) dst[m][k] = *(const PG8_LAS bf16x8*)(lds + PG8_SA(b, h) + aoff + m * 2048 + k * 1024); } while (0)
; #define PG8_LDB(dst, b, h) do { _Pragma("unroll") for (int n = 0; n < 2; ++n) _Pragma("unroll") for (int k = 0; k < 2; ++k) dst[n][k] = *(const PG8_LAS bf16x8*)(lds + PG8_SB(b, h) + boff + n * 2048 + k * 1024); } while (0)
; #define PG8_MMA(ai, bj, At, Bt) do { __builtin_amdgcn_s_setprio(1); _Pragma("unroll") for (int m = 0; m < 4; ++m) _Pragma("unroll") for (int n = 0; n < 2; ++n) _Pragma("unroll") for (int k = 0; k < 2; ++k) \
;         acc[ai][bj][m][n] = __builtin_amdgcn_mfma_f32_16x16x32_bf16(Bt[n][k], At[m][k], acc[ai][bj][m][n], 0, 0, 0); __builtin_amdgcn_s_setprio(0); } while (0)
; #define PG8_BAR __builtin_amdgcn_s_barrier()
; template <class Epi, class Sched, bool ALIGN_EPI = false, bool SP2 = false>
; __device__ __forceinline__ void gemm_phase(PG8_LAS unsigned char* lds, const Gemm g, const Sched& S, const Epi& E) {
;     ...
;             if constexpr (SP2) {
;             PG8_LDB(B0, 0, 0); PG8_LDB(B1, 0, 1); PG8_SCHED; PG8_LDA(At, 0, 0); PG8_STAGE(PG8_SA(1, 1), a1 + hstep, voffA);
;             PG8_WAIT_V(8); PG8_WAIT_L(0); PG8_BAR; PG8_MMA(0, 0, At, B0); PG8_MMA(0, 1, At, B1); PG8_BAR; PG8_SCHED;
;             PG8_LDA(At, 0, 1); PG8_STAGE(PG8_SB(0, 0), b2, voffB); PG8_STAGE(PG8_SB(0, 1), b2 + hstep, voffB); PG8_STAGE(PG8_SA(0, 0), a2, voffA);
;             PG8_WAIT_V(8); PG8_WAIT_L(0); PG8_BAR; PG8_MMA(1, 0, At, B0); PG8_MMA(1, 1, At, B1); PG8_BAR; PG8_SCHED;
;             PG8_LDB(B0, 1, 0); PG8_LDB(B1, 1, 1); PG8_SCHED; PG8_LDA(At, 1, 0); PG8_STAGE(PG8_SA(0, 1), a2 + hstep, voffA);
;             PG8_WAIT_V(8); PG8_WAIT_L(0); PG8_BAR; PG8_MMA(0, 0, At, B0); PG8_MMA(0, 1, At, B1); PG8_BAR; PG8_SCHED;
;             PG8_LDA(At, 1, 1); PG8_STAGE(PG8_SB(1, 0), b3, voffB); PG8_STAGE(PG8_SB(1, 1), b3 + hstep, voffB); PG8_STAGE(PG8_SA(1, 0), a3, voffA);
;             PG8_WAIT_V(8); PG8_WAIT_L(0); PG8_BAR; PG8_MMA(1, 0, At, B0); PG8_MMA(1, 1, At, B1); PG8_BAR; PG8_SCHED;
.Lip_h1first:
	ds_read_b128 v[150:153], v169
	ds_read_b128 v[154:157], v169 offset:1024
	ds_read_b128 v[158:161], v169 offset:2048
	ds_read_b128 v[162:165], v169 offset:3072
	ds_read_b128 v[174:177], v170
	ds_read_b128 v[178:181], v170 offset:1024
	ds_read_b128 v[182:185], v170 offset:2048
	ds_read_b128 v[186:189], v170 offset:3072
	s_add_u32 s0, s88, 0xfff00080
	s_addc_u32 s1, s89, -1
	s_cmp_eq_u32 s23, 60
	s_cselect_b32 s93, s51, s1
	s_cselect_b32 s92, s50, s0
	s_cselect_b32 s91, s53, s21
	s_cselect_b32 s90, s52, s9
	ds_read_b128 v[190:193], v171
	ds_read_b128 v[196:199], v171 offset:1024
	ds_read_b128 v[200:203], v171 offset:2048
	ds_read_b128 v[204:207], v171 offset:3072
	ds_read_b128 v[208:211], v171 offset:4096
	ds_read_b128 v[212:215], v171 offset:5120
	ds_read_b128 v[220:223], v171 offset:6144
	ds_read_b128 v[224:227], v171 offset:7168
	s_add_u32 s0, s88, 0xfff00000
	s_addc_u32 s1, s89, -1
	s_add_i32 m0, s27, 0x8000
	s_nop 0
	global_load_lds_dwordx4 v134, s[0:1]
	s_add_i32 m0, s27, 0xa000
	s_nop 0
	global_load_lds_dwordx4 v138, s[0:1]
	s_add_i32 m0, s27, 0xc000
	s_nop 0
	global_load_lds_dwordx4 v134, s[88:89]
	s_add_i32 m0, s27, 0xe000
	s_nop 0
	global_load_lds_dwordx4 v138, s[88:89]
	s_sleep 2
	s_waitcnt lgkmcnt(0)
	s_waitcnt vmcnt(8)
	s_barrier
	s_setprio 2
	v_mfma_f32_16x16x32_bf16 v[38:41], v[150:153], v[190:193], 0
	v_mfma_f32_16x16x32_bf16 v[30:33], v[158:161], v[190:193], 0
	v_mfma_f32_16x16x32_bf16 v[130:133], v[150:153], v[200:203], 0
	v_mfma_f32_16x16x32_bf16 v[126:129], v[158:161], v[200:203], 0
	v_mfma_f32_16x16x32_bf16 v[114:117], v[150:153], v[208:211], 0
	v_mfma_f32_16x16x32_bf16 v[110:113], v[158:161], v[208:211], 0
	v_mfma_f32_16x16x32_bf16 v[98:101], v[150:153], v[220:223], 0
	v_mfma_f32_16x16x32_bf16 v[94:97], v[158:161], v[220:223], 0
	v_mfma_f32_16x16x32_bf16 v[38:41], v[154:157], v[196:199], v[38:41]
	v_mfma_f32_16x16x32_bf16 v[30:33], v[162:165], v[196:199], v[30:33]
	v_mfma_f32_16x16x32_bf16 v[130:133], v[154:157], v[204:207], v[130:133]
	v_mfma_f32_16x16x32_bf16 v[126:129], v[162:165], v[204:207], v[126:129]
	v_mfma_f32_16x16x32_bf16 v[114:117], v[154:157], v[212:215], v[114:117]
	v_mfma_f32_16x16x32_bf16 v[110:113], v[162:165], v[212:215], v[110:113]
	v_mfma_f32_16x16x32_bf16 v[98:101], v[154:157], v[224:227], v[98:101]
	v_mfma_f32_16x16x32_bf16 v[94:97], v[162:165], v[224:227], v[94:97]
	v_mfma_f32_16x16x32_bf16 v[50:53], v[174:177], v[190:193], 0
	v_mfma_f32_16x16x32_bf16 v[46:49], v[182:185], v[190:193], 0
	v_mfma_f32_16x16x32_bf16 v[122:125], v[174:177], v[200:203], 0
	v_mfma_f32_16x16x32_bf16 v[118:121], v[182:185], v[200:203], 0
	v_mfma_f32_16x16x32_bf16 v[106:109], v[174:177], v[208:211], 0
	v_mfma_f32_16x16x32_bf16 v[102:105], v[182:185], v[208:211], 0
	v_mfma_f32_16x16x32_bf16 v[90:93], v[174:177], v[220:223], 0
	v_mfma_f32_16x16x32_bf16 v[86:89], v[182:185], v[220:223], 0
	v_mfma_f32_16x16x32_bf16 v[50:53], v[178:181], v[196:199], v[50:53]
	v_mfma_f32_16x16x32_bf16 v[46:49], v[186:189], v[196:199], v[46:49]
	v_mfma_f32_16x16x32_bf16 v[122:125], v[178:181], v[204:207], v[122:125]
	v_mfma_f32_16x16x32_bf16 v[118:121], v[186:189], v[204:207], v[118:121]
	v_mfma_f32_16x16x32_bf16 v[106:109], v[178:181], v[212:215], v[106:109]
	v_mfma_f32_16x16x32_bf16 v[102:105], v[186:189], v[212:215], v[102:105]
	v_mfma_f32_16x16x32_bf16 v[90:93], v[178:181], v[224:227], v[90:93]
	v_mfma_f32_16x16x32_bf16 v[86:89], v[186:189], v[224:227], v[86:89]
	s_setprio 0
	ds_read_b128 v[190:193], v171 offset:16384
	ds_read_b128 v[196:199], v171 offset:17408
	ds_read_b128 v[200:203], v171 offset:18432
	ds_read_b128 v[204:207], v171 offset:19456
	ds_read_b128 v[208:211], v171 offset:20480
	ds_read_b128 v[212:215], v171 offset:21504
	ds_read_b128 v[220:223], v171 offset:22528
	ds_read_b128 v[224:227], v171 offset:23552
	s_add_u32 vcc_lo, s90, 0x100000
	s_addc_u32 vcc_hi, s91, 0
	s_add_i32 m0, s27, 0x10000
	s_nop 0
	global_load_lds_dwordx4 v136, s[90:91]
	s_add_i32 m0, s27, 0x12000
	s_nop 0
	global_load_lds_dwordx4 v140, s[90:91]
	s_add_i32 m0, s27, 0x14000
	s_nop 0
	global_load_lds_dwordx4 v136, vcc
	s_add_i32 m0, s27, 0x16000
	s_nop 0
	global_load_lds_dwordx4 v140, vcc
	s_sleep 2
	s_waitcnt lgkmcnt(0)
	s_waitcnt vmcnt(6)
	s_barrier
	s_setprio 2
	v_mfma_f32_16x16x32_bf16 v[82:85], v[150:153], v[190:193], 0
	v_mfma_f32_16x16x32_bf16 v[78:81], v[158:161], v[190:193], 0
	v_mfma_f32_16x16x32_bf16 v[66:69], v[150:153], v[200:203], 0
	v_mfma_f32_16x16x32_bf16 v[62:65], v[158:161], v[200:203], 0
	v_mfma_f32_16x16x32_bf16 v[42:45], v[150:153], v[208:211], 0
	v_mfma_f32_16x16x32_bf16 v[34:37], v[158:161], v[208:211], 0
	v_mfma_f32_16x16x32_bf16 v[18:21], v[150:153], v[220:223], 0
	v_mfma_f32_16x16x32_bf16 v[14:17], v[158:161], v[220:223], 0
	v_mfma_f32_16x16x32_bf16 v[82:85], v[154:157], v[196:199], v[82:85]
	v_mfma_f32_16x16x32_bf16 v[78:81], v[162:165], v[196:199], v[78:81]
	v_mfma_f32_16x16x32_bf16 v[66:69], v[154:157], v[204:207], v[66:69]
	v_mfma_f32_16x16x32_bf16 v[62:65], v[162:165], v[204:207], v[62:65]
	v_mfma_f32_16x16x32_bf16 v[42:45], v[154:157], v[212:215], v[42:45]
	v_mfma_f32_16x16x32_bf16 v[34:37], v[162:165], v[212:215], v[34:37]
	v_mfma_f32_16x16x32_bf16 v[18:21], v[154:157], v[224:227], v[18:21]
	v_mfma_f32_16x16x32_bf16 v[14:17], v[162:165], v[224:227], v[14:17]
	v_mfma_f32_16x16x32_bf16 v[74:77], v[174:177], v[190:193], 0
	v_mfma_f32_16x16x32_bf16 v[70:73], v[182:185], v[190:193], 0
	v_mfma_f32_16x16x32_bf16 v[58:61], v[174:177], v[200:203], 0
	v_mfma_f32_16x16x32_bf16 v[54:57], v[182:185], v[200:203], 0
	v_mfma_f32_16x16x32_bf16 v[26:29], v[174:177], v[208:211], 0
	v_mfma_f32_16x16x32_bf16 v[22:25], v[182:185], v[208:211], 0
; #define PG8_STAGE(bufoff, gbase, voff) do { _Pragma("unroll") for (int _i = 0; _i < 2; ++_i) \
;         __builtin_amdgcn_global_load_lds((const unsigned*)((const char*)(gbase) + (voff)[_i]), (PG8_LAS unsigned*)(lds + (bufoff) + ldsw + _i * 8192), 16, 0, 0); } while (0)
; #define PG8_LDA(dst, b, h) do { _Pragma("unroll") for (int m = 0; m < 4; ++m) _Pragma("unroll") for (int k = 0; k < 2; ++k) dst[m][k] = *(const PG8_LAS bf16x8*)(lds + PG8_SA(b, h) + aoff + m * 2048 + k * 1024); } while (0)
; #define PG8_LDB(dst, b, h) do { _Pragma("unroll") for (int n = 0; n < 2; ++n) _Pragma("unroll") for (int k = 0; k < 2; ++k) dst[n][k] = *(const PG8_LAS bf16x8*)(lds + PG8_SB(b, h) + boff + n * 2048 + k * 1024); } while (0)
; #define PG8_MMA(ai, bj, At, Bt) do { __builtin_amdgcn_s_setprio(1); _Pragma("unroll") for (int m = 0; m < 4; ++m) _Pragma("unroll") for (int n = 0; n < 2; ++n) _Pragma("unroll") for (int k = 0; k < 2; ++k) \
;         acc[ai][bj][m][n] = __builtin_amdgcn_mfma_f32_16x16x32_bf16(Bt[n][k], At[m][k], acc[ai][bj][m][n], 0, 0, 0); __builtin_amdgcn_s_setprio(0); } while (0)
; #define PG8_BAR __builtin_amdgcn_s_barrier()
; template <class Epi, class Sched, bool ALIGN_EPI = false, bool SP2 = false>
; __device__ __forceinline__ void gemm_phase(PG8_LAS unsigned char* lds, const Gemm g, const Sched& S, const Epi& E) {
;     ...
;             if constexpr (SP2) {
;             PG8_LDB(B0, 0, 0); PG8_LDB(B1, 0, 1); PG8_SCHED; PG8_LDA(At, 0, 0); PG8_STAGE(PG8_SA(1, 1), a1 + hstep, voffA);
;             PG8_WAIT_V(8); PG8_WAIT_L(0); PG8_BAR; PG8_MMA(0, 0, At, B0); PG8_MMA(0, 1, At, B1); PG8_BAR; PG8_SCHED;
;             PG8_LDA(At, 0, 1); PG8_STAGE(PG8_SB(0, 0), b2, voffB); PG8_STAGE(PG8_SB(0, 1), b2 + hstep, voffB); PG8_STAGE(PG8_SA(0, 0), a2, voffA);
;             PG8_WAIT_V(8); PG8_WAIT_L(0); PG8_BAR; PG8_MMA(1, 0, At, B0); PG8_MMA(1, 1, At, B1); PG8_BAR; PG8_SCHED;
;             PG8_LDB(B0, 1, 0); PG8_LDB(B1, 1, 1); PG8_SCHED; PG8_LDA(At, 1, 0); PG8_STAGE(PG8_SA(0, 1), a2 + hstep, voffA);
;             PG8_WAIT_V(8); PG8_WAIT_L(0); PG8_BAR; PG8_MMA(0, 0, At, B0); PG8_MMA(0, 1, At, B1); PG8_BAR; PG8_SCHED;
;             PG8_LDA(At, 1, 1); PG8_STAGE(PG8_SB(1, 0), b3, voffB); PG8_STAGE(PG8_SB(1, 1), b3 + hstep, voffB); PG8_STAGE(PG8_SA(1, 0), a3, voffA);
;             PG8_WAIT_V(8); PG8_WAIT_L(0); PG8_BAR; PG8_MMA(1, 0, At, B0); PG8_MMA(1, 1, At, B1); PG8_BAR; PG8_SCHED;
	v_mfma_f32_16x16x32_bf16 v[10:13], v[174:177], v[220:223], 0
	v_mfma_f32_16x16x32_bf16 v[4:7], v[182:185], v[220:223], 0
	v_mfma_f32_16x16x32_bf16 v[74:77], v[178:181], v[196:199], v[74:77]
	v_mfma_f32_16x16x32_bf16 v[70:73], v[186:189], v[196:199], v[70:73]
	v_mfma_f32_16x16x32_bf16 v[58:61], v[178:181], v[204:207], v[58:61]
	v_mfma_f32_16x16x32_bf16 v[54:57], v[186:189], v[204:207], v[54:57]
	v_mfma_f32_16x16x32_bf16 v[26:29], v[178:181], v[212:215], v[26:29]
	v_mfma_f32_16x16x32_bf16 v[22:25], v[186:189], v[212:215], v[22:25]
	v_mfma_f32_16x16x32_bf16 v[10:13], v[178:181], v[224:227], v[10:13]
	v_mfma_f32_16x16x32_bf16 v[4:7], v[186:189], v[224:227], v[4:7]
	s_setprio 0
	s_add_i32 s0, 0, 0x18000
	v_add_u32_e32 v3, s0, v167
	s_add_i32 s1, 0, 0x1c000
	ds_read_b128 v[150:153], v3
	ds_read_b128 v[154:157], v3 offset:1024
	ds_read_b128 v[158:161], v3 offset:2048
	ds_read_b128 v[162:165], v3 offset:3072
	v_add_u32_e32 v3, s1, v167
	ds_read_b128 v[174:177], v3
	ds_read_b128 v[178:181], v3 offset:1024
	ds_read_b128 v[182:185], v3 offset:2048
	ds_read_b128 v[186:189], v3 offset:3072
	ds_read_b128 v[190:193], v171 offset:32768
	ds_read_b128 v[196:199], v171 offset:33792
	ds_read_b128 v[200:203], v171 offset:34816
	ds_read_b128 v[204:207], v171 offset:35840
	ds_read_b128 v[208:211], v171 offset:36864
	ds_read_b128 v[212:215], v171 offset:37888
	ds_read_b128 v[220:223], v171 offset:38912
	ds_read_b128 v[224:227], v171 offset:39936
	s_add_u32 vcc_lo, s92, 0x100000
	s_addc_u32 vcc_hi, s93, 0
	s_mov_b32 m0, s27
	s_nop 0
	global_load_lds_dwordx4 v134, s[92:93]
	s_add_i32 m0, s27, 0x2000
	s_nop 0
	global_load_lds_dwordx4 v138, s[92:93]
	s_add_i32 m0, s27, 0x4000
	s_nop 0
	global_load_lds_dwordx4 v134, vcc
	s_add_i32 m0, s27, 0x6000
	s_nop 0
	global_load_lds_dwordx4 v138, vcc
	s_sleep 2
	s_waitcnt lgkmcnt(0)
	s_waitcnt vmcnt(8)
	s_barrier
	s_setprio 2
	v_mfma_f32_16x16x32_bf16 v[38:41], v[150:153], v[190:193], v[38:41]
	v_mfma_f32_16x16x32_bf16 v[30:33], v[158:161], v[190:193], v[30:33]
	v_mfma_f32_16x16x32_bf16 v[130:133], v[150:153], v[200:203], v[130:133]
	v_mfma_f32_16x16x32_bf16 v[126:129], v[158:161], v[200:203], v[126:129]
	v_mfma_f32_16x16x32_bf16 v[114:117], v[150:153], v[208:211], v[114:117]
	v_mfma_f32_16x16x32_bf16 v[110:113], v[158:161], v[208:211], v[110:113]
	v_mfma_f32_16x16x32_bf16 v[98:101], v[150:153], v[220:223], v[98:101]
	v_mfma_f32_16x16x32_bf16 v[94:97], v[158:161], v[220:223], v[94:97]
	v_mfma_f32_16x16x32_bf16 v[38:41], v[154:157], v[196:199], v[38:41]
	v_mfma_f32_16x16x32_bf16 v[30:33], v[162:165], v[196:199], v[30:33]
	v_mfma_f32_16x16x32_bf16 v[130:133], v[154:157], v[204:207], v[130:133]
	v_mfma_f32_16x16x32_bf16 v[126:129], v[162:165], v[204:207], v[126:129]
	v_mfma_f32_16x16x32_bf16 v[114:117], v[154:157], v[212:215], v[114:117]
	v_mfma_f32_16x16x32_bf16 v[110:113], v[162:165], v[212:215], v[110:113]
	v_mfma_f32_16x16x32_bf16 v[98:101], v[154:157], v[224:227], v[98:101]
	v_mfma_f32_16x16x32_bf16 v[94:97], v[162:165], v[224:227], v[94:97]
	v_mfma_f32_16x16x32_bf16 v[50:53], v[174:177], v[190:193], v[50:53]
	v_mfma_f32_16x16x32_bf16 v[46:49], v[182:185], v[190:193], v[46:49]
	v_mfma_f32_16x16x32_bf16 v[122:125], v[174:177], v[200:203], v[122:125]
	v_mfma_f32_16x16x32_bf16 v[118:121], v[182:185], v[200:203], v[118:121]
	v_mfma_f32_16x16x32_bf16 v[106:109], v[174:177], v[208:211], v[106:109]
	v_mfma_f32_16x16x32_bf16 v[102:105], v[182:185], v[208:211], v[102:105]
	v_mfma_f32_16x16x32_bf16 v[90:93], v[174:177], v[220:223], v[90:93]
	v_mfma_f32_16x16x32_bf16 v[86:89], v[182:185], v[220:223], v[86:89]
	v_mfma_f32_16x16x32_bf16 v[50:53], v[178:181], v[196:199], v[50:53]
	v_mfma_f32_16x16x32_bf16 v[46:49], v[186:189], v[196:199], v[46:49]
	v_mfma_f32_16x16x32_bf16 v[122:125], v[178:181], v[204:207], v[122:125]
	v_mfma_f32_16x16x32_bf16 v[118:121], v[186:189], v[204:207], v[118:121]
	v_mfma_f32_16x16x32_bf16 v[106:109], v[178:181], v[212:215], v[106:109]
	v_mfma_f32_16x16x32_bf16 v[102:105], v[186:189], v[212:215], v[102:105]
	v_mfma_f32_16x16x32_bf16 v[90:93], v[178:181], v[224:227], v[90:93]
	v_mfma_f32_16x16x32_bf16 v[86:89], v[186:189], v[224:227], v[86:89]
	s_setprio 0
	ds_read_b128 v[190:193], v171 offset:49152
	ds_read_b128 v[196:199], v171 offset:50176
	ds_read_b128 v[200:203], v171 offset:51200
	ds_read_b128 v[204:207], v171 offset:52224
	ds_read_b128 v[208:211], v171 offset:53248
	ds_read_b128 v[212:215], v171 offset:54272
	ds_read_b128 v[220:223], v171 offset:55296
	ds_read_b128 v[224:227], v171 offset:56320
	s_add_u32 s0, s90, 0x80
	s_addc_u32 s1, s91, 0
	s_add_u32 vcc_lo, s0, 0x100000
	s_addc_u32 vcc_hi, s1, 0
	s_add_i32 m0, s27, 0x18000
	s_nop 0
	global_load_lds_dwordx4 v136, s[0:1]
	s_add_i32 m0, s27, 0x1a000
	s_nop 0
	global_load_lds_dwordx4 v140, s[0:1]
	s_add_i32 m0, s27, 0x1c000
	s_nop 0
	global_load_lds_dwordx4 v136, vcc
	s_add_i32 m0, s27, 0x1e000
	s_nop 0
	global_load_lds_dwordx4 v140, vcc
	s_sleep 2
	s_waitcnt lgkmcnt(0)
	s_waitcnt vmcnt(6)
	s_barrier
; #define PG8_STAGE(bufoff, gbase, voff) do { _Pragma("unroll") for (int _i = 0; _i < 2; ++_i) \
;         __builtin_amdgcn_global_load_lds((const unsigned*)((const char*)(gbase) + (voff)[_i]), (PG8_LAS unsigned*)(lds + (bufoff) + ldsw + _i * 8192), 16, 0, 0); } while (0)
; #define PG8_LDA(dst, b, h) do { _Pragma("unroll") for (int m = 0; m < 4; ++m) _Pragma("unroll") for (int k = 0; k < 2; ++k) dst[m][k] = *(const PG8_LAS bf16x8*)(lds + PG8_SA(b, h) + aoff + m * 2048 + k * 1024); } while (0)
; #define PG8_LDB(dst, b, h) do { _Pragma("unroll") for (int n = 0; n < 2; ++n) _Pragma("unroll") for (int k = 0; k < 2; ++k) dst[n][k] = *(const PG8_LAS bf16x8*)(lds + PG8_SB(b, h) + boff + n * 2048 + k * 1024); } while (0)
; #define PG8_MMA(ai, bj, At, Bt) do { __builtin_amdgcn_s_setprio(1); _Pragma("unroll") for (int m = 0; m < 4; ++m) _Pragma("unroll") for (int n = 0; n < 2; ++n) _Pragma("unroll") for (int k = 0; k < 2; ++k) \
;         acc[ai][bj][m][n] = __builtin_amdgcn_mfma_f32_16x16x32_bf16(Bt[n][k], At[m][k], acc[ai][bj][m][n], 0, 0, 0); __builtin_amdgcn_s_setprio(0); } while (0)
; #define PG8_BAR __builtin_amdgcn_s_barrier()
; template <class Epi, class Sched, bool ALIGN_EPI = false, bool SP2 = false>
; __device__ __forceinline__ void gemm_phase(PG8_LAS unsigned char* lds, const Gemm g, const Sched& S, const Epi& E) {
;     ...
;             if constexpr (SP2) {
;             PG8_LDB(B0, 0, 0); PG8_LDB(B1, 0, 1); PG8_SCHED; PG8_LDA(At, 0, 0); PG8_STAGE(PG8_SA(1, 1), a1 + hstep, voffA);
;             PG8_WAIT_V(8); PG8_WAIT_L(0); PG8_BAR; PG8_MMA(0, 0, At, B0); PG8_MMA(0, 1, At, B1); PG8_BAR; PG8_SCHED;
;             PG8_LDA(At, 0, 1); PG8_STAGE(PG8_SB(0, 0), b2, voffB); PG8_STAGE(PG8_SB(0, 1), b2 + hstep, voffB); PG8_STAGE(PG8_SA(0, 0), a2, voffA);
;             PG8_WAIT_V(8); PG8_WAIT_L(0); PG8_BAR; PG8_MMA(1, 0, At, B0); PG8_MMA(1, 1, At, B1); PG8_BAR; PG8_SCHED;
;             PG8_LDB(B0, 1, 0); PG8_LDB(B1, 1, 1); PG8_SCHED; PG8_LDA(At, 1, 0); PG8_STAGE(PG8_SA(0, 1), a2 + hstep, voffA);
;             PG8_WAIT_V(8); PG8_WAIT_L(0); PG8_BAR; PG8_MMA(0, 0, At, B0); PG8_MMA(0, 1, At, B1); PG8_BAR; PG8_SCHED;
;             PG8_LDA(At, 1, 1); PG8_STAGE(PG8_SB(1, 0), b3, voffB); PG8_STAGE(PG8_SB(1, 1), b3 + hstep, voffB); PG8_STAGE(PG8_SA(1, 0), a3, voffA);
;             PG8_WAIT_V(8); PG8_WAIT_L(0); PG8_BAR; PG8_MMA(1, 0, At, B0); PG8_MMA(1, 1, At, B1); PG8_BAR; PG8_SCHED;
	s_setprio 2
	v_mfma_f32_16x16x32_bf16 v[82:85], v[150:153], v[190:193], v[82:85]
	v_mfma_f32_16x16x32_bf16 v[78:81], v[158:161], v[190:193], v[78:81]
	v_mfma_f32_16x16x32_bf16 v[66:69], v[150:153], v[200:203], v[66:69]
	v_mfma_f32_16x16x32_bf16 v[62:65], v[158:161], v[200:203], v[62:65]
	v_mfma_f32_16x16x32_bf16 v[42:45], v[150:153], v[208:211], v[42:45]
	v_mfma_f32_16x16x32_bf16 v[34:37], v[158:161], v[208:211], v[34:37]
	v_mfma_f32_16x16x32_bf16 v[18:21], v[150:153], v[220:223], v[18:21]
	v_mfma_f32_16x16x32_bf16 v[14:17], v[158:161], v[220:223], v[14:17]
	v_mfma_f32_16x16x32_bf16 v[82:85], v[154:157], v[196:199], v[82:85]
	v_mfma_f32_16x16x32_bf16 v[78:81], v[162:165], v[196:199], v[78:81]
	v_mfma_f32_16x16x32_bf16 v[66:69], v[154:157], v[204:207], v[66:69]
	v_mfma_f32_16x16x32_bf16 v[62:65], v[162:165], v[204:207], v[62:65]
	v_mfma_f32_16x16x32_bf16 v[42:45], v[154:157], v[212:215], v[42:45]
	v_mfma_f32_16x16x32_bf16 v[34:37], v[162:165], v[212:215], v[34:37]
	v_mfma_f32_16x16x32_bf16 v[18:21], v[154:157], v[224:227], v[18:21]
	v_mfma_f32_16x16x32_bf16 v[14:17], v[162:165], v[224:227], v[14:17]
	v_mfma_f32_16x16x32_bf16 v[74:77], v[174:177], v[190:193], v[74:77]
	v_mfma_f32_16x16x32_bf16 v[70:73], v[182:185], v[190:193], v[70:73]
	v_mfma_f32_16x16x32_bf16 v[58:61], v[174:177], v[200:203], v[58:61]
	v_mfma_f32_16x16x32_bf16 v[54:57], v[182:185], v[200:203], v[54:57]
	v_mfma_f32_16x16x32_bf16 v[26:29], v[174:177], v[208:211], v[26:29]
	v_mfma_f32_16x16x32_bf16 v[22:25], v[182:185], v[208:211], v[22:25]
	v_mfma_f32_16x16x32_bf16 v[8:11], v[174:177], v[220:223], v[10:13]
	v_mfma_f32_16x16x32_bf16 v[4:7], v[182:185], v[220:223], v[4:7]
	v_mfma_f32_16x16x32_bf16 v[74:77], v[178:181], v[196:199], v[74:77]
	v_mfma_f32_16x16x32_bf16 v[70:73], v[186:189], v[196:199], v[70:73]
	v_mfma_f32_16x16x32_bf16 v[58:61], v[178:181], v[204:207], v[58:61]
	v_mfma_f32_16x16x32_bf16 v[54:57], v[186:189], v[204:207], v[54:57]
	v_mfma_f32_16x16x32_bf16 v[26:29], v[178:181], v[212:215], v[26:29]
	v_mfma_f32_16x16x32_bf16 v[22:25], v[186:189], v[212:215], v[22:25]
	v_mfma_f32_16x16x32_bf16 v[10:13], v[178:181], v[224:227], v[8:11]
	v_mfma_f32_16x16x32_bf16 v[6:9], v[186:189], v[224:227], v[4:7]
	s_setprio 0
	s_add_i32 s23, s23, 2
	s_add_u32 s88, s88, 0x100
	s_addc_u32 s89, s89, 0
	s_add_u32 s9, s9, 0x100
	s_addc_u32 s21, s21, 0
	s_cmp_gt_u32 s23, 61

;     __device__ __forceinline__ bool next(int i, Unit& u) const { const long L = (long)i * G + c; if (L >= nwg) return false; std_map((int)L, nM, nN, u, wgm); u.ui = i; return true; }
;     __device__ __forceinline__ bool next(int i, Unit& u) const { if (i >= 4) return false; const int x = c & 7, r = c >> 3; u.pm = 16 * i + 4 * (x >> 1) + (r & 3); u.pn = 8 * (x & 1) + (r >> 2); u.ui = i; return true; }
; #define PG8_LDA(dst, b, h) do { _Pragma("unroll") for (int m = 0; m < 4; ++m) _Pragma("unroll") for (int k = 0; k < 2; ++k) dst[m][k] = *(const PG8_LAS bf16x8*)(lds + PG8_SA(b, h) + aoff + m * 2048 + k * 1024); } while (0)
; template <class Epi, class Sched, bool ALIGN_EPI = false, bool SP2 = false>
; __device__ __forceinline__ void gemm_phase(PG8_LAS unsigned char* lds, const Gemm g, const Sched& S, const Epi& E) {
;     ...
;         const bool has_next = S.next(ui + 1, nxt);
;         const char* nA = cA; const char* nB = cB; if (has_next) S.bases(nxt, g, tstep, nA, nB);
;     ...
;             if constexpr (SP2) {
;             PG8_LDB(B0, 0, 0); PG8_LDB(B1, 0, 1); PG8_SCHED; PG8_LDA(At, 0, 0); PG8_STAGE(PG8_SA(1, 1), a1 + hstep, voffA);
;             PG8_WAIT_V(8); PG8_WAIT_L(0); PG8_BAR; PG8_MMA(0, 0, At, B0); PG8_MMA(0, 1, At, B1); PG8_BAR; PG8_SCHED;
;             PG8_LDA(At, 0, 1); PG8_STAGE(PG8_SB(0, 0), b2, voffB); PG8_STAGE(PG8_SB(0, 1), b2 + hstep, voffB); PG8_STAGE(PG8_SA(0, 0), a2, voffA);
;             PG8_WAIT_V(8); PG8_WAIT_L(0); PG8_BAR; PG8_MMA(1, 0, At, B0); PG8_MMA(1, 1, At, B1); PG8_BAR; PG8_SCHED;
;             PG8_LDB(B0, 1, 0); PG8_LDB(B1, 1, 1); PG8_SCHED; PG8_LDA(At, 1, 0); PG8_STAGE(PG8_SA(0, 1), a2 + hstep, voffA);
;             PG8_WAIT_V(8); PG8_WAIT_L(0); PG8_BAR; PG8_MMA(0, 0, At, B0); PG8_MMA(0, 1, At, B1); PG8_BAR; PG8_SCHED;
;             PG8_LDA(At, 1, 1); PG8_STAGE(PG8_SB(1, 0), b3, voffB); PG8_STAGE(PG8_SB(1, 1), b3 + hstep, voffB); PG8_STAGE(PG8_SA(1, 0), a3, voffA);
;             PG8_WAIT_V(8); PG8_WAIT_L(0); PG8_BAR; PG8_MMA(1, 0, At, B0); PG8_MMA(1, 1, At, B1); PG8_BAR; PG8_SCHED;
;     ...
; #pragma unroll
;         for (int a = 0; a < 2; ++a)
; #pragma unroll
;             for (int b = 0; b < 2; ++b)
; #pragma unroll
;                 for (int m = 0; m < 4; ++m)
; #pragma unroll
;                     for (int n = 0; n < 2; ++n) acc[a][b][m][n] = (f32x4){0.f, 0.f, 0.f, 0.f};
;         cur = nxt; cA = nA; cB = nB; ++ui;
.LBB0_1250:
	s_ashr_i32 s17, s16, 31
	s_lshl_b64 s[18:19], s[16:17], 21
	s_add_u32 s18, s34, s18
	s_addc_u32 s19, s35, s19
	s_ashr_i32 s15, s14, 31
	s_lshl_b64 s[20:21], s[14:15], 21
	s_add_u32 s20, s30, s20
	s_addc_u32 s21, s31, s21
	s_and_b64 s[42:43], s[4:5], exec
	s_cselect_b32 s15, s19, s37
	s_cselect_b32 s17, s18, s36
	s_cselect_b32 s54, s21, s41
	s_cselect_b32 s55, s20, s40
	s_add_u32 s36, s36, 0x100080
	s_addc_u32 s37, s37, 0
	s_add_u32 s56, s40, 0x100
	s_addc_u32 s57, s41, 0
	s_mov_b32 s58, -2
	s_cmp_lt_u32 s24, 0x1000
	s_cbranch_scc0 .Lf1_h1first
	ds_read_b128 v[130:133], v177
	ds_read_b128 v[134:137], v177 offset:1024
	ds_read_b128 v[138:141], v177 offset:2048
	ds_read_b128 v[142:145], v177 offset:3072
	ds_read_b128 v[162:165], v178
	ds_read_b128 v[180:183], v178 offset:1024
	ds_read_b128 v[184:187], v178 offset:2048
	ds_read_b128 v[188:191], v178 offset:3072
	s_add_u32 s40, s36, 0xfff00080
	s_addc_u32 s41, s37, -1
	s_cmp_eq_u32 s58, 60
	s_cselect_b32 s43, s15, s41
	s_cselect_b32 s42, s17, s40
	s_cselect_b32 s41, s54, s57
	s_cselect_b32 s40, s55, s56
	ds_read_b128 v[196:199], v179
	ds_read_b128 v[200:203], v179 offset:1024
	ds_read_b128 v[204:207], v179 offset:2048
	ds_read_b128 v[208:211], v179 offset:3072
	ds_read_b128 v[212:215], v179 offset:4096
	ds_read_b128 v[220:223], v179 offset:5120
	ds_read_b128 v[224:227], v179 offset:6144
	ds_read_b128 v[228:231], v179 offset:7168
	s_add_i32 m0, s24, 0xc000
	s_nop 0
	global_load_lds_dwordx4 v146, s[36:37]
	s_add_i32 m0, s24, 0xe000
	s_nop 0
	global_load_lds_dwordx4 v150, s[36:37]
	s_waitcnt lgkmcnt(0)
	s_setprio 1
	v_mfma_f32_16x16x32_bf16 v[126:129], v[130:133], v[196:199], 0
	v_mfma_f32_16x16x32_bf16 v[122:125], v[138:141], v[196:199], 0
	v_mfma_f32_16x16x32_bf16 v[110:113], v[130:133], v[204:207], 0
	v_mfma_f32_16x16x32_bf16 v[106:109], v[138:141], v[204:207], 0
	v_mfma_f32_16x16x32_bf16 v[94:97], v[130:133], v[212:215], 0
	v_mfma_f32_16x16x32_bf16 v[90:93], v[138:141], v[212:215], 0
	v_mfma_f32_16x16x32_bf16 v[78:81], v[130:133], v[224:227], 0
	v_mfma_f32_16x16x32_bf16 v[74:77], v[138:141], v[224:227], 0
	v_mfma_f32_16x16x32_bf16 v[126:129], v[134:137], v[200:203], v[126:129]
	v_mfma_f32_16x16x32_bf16 v[122:125], v[142:145], v[200:203], v[122:125]
	v_mfma_f32_16x16x32_bf16 v[110:113], v[134:137], v[208:211], v[110:113]
	v_mfma_f32_16x16x32_bf16 v[106:109], v[142:145], v[208:211], v[106:109]
	v_mfma_f32_16x16x32_bf16 v[94:97], v[134:137], v[220:223], v[94:97]
	v_mfma_f32_16x16x32_bf16 v[90:93], v[142:145], v[220:223], v[90:93]
	v_mfma_f32_16x16x32_bf16 v[78:81], v[134:137], v[228:231], v[78:81]
	v_mfma_f32_16x16x32_bf16 v[74:77], v[142:145], v[228:231], v[74:77]
	v_mfma_f32_16x16x32_bf16 v[118:121], v[162:165], v[196:199], 0
	v_mfma_f32_16x16x32_bf16 v[114:117], v[184:187], v[196:199], 0
	v_mfma_f32_16x16x32_bf16 v[102:105], v[162:165], v[204:207], 0
	v_mfma_f32_16x16x32_bf16 v[98:101], v[184:187], v[204:207], 0
	v_mfma_f32_16x16x32_bf16 v[86:89], v[162:165], v[212:215], 0
	v_mfma_f32_16x16x32_bf16 v[82:85], v[184:187], v[212:215], 0
	v_mfma_f32_16x16x32_bf16 v[70:73], v[162:165], v[224:227], 0
	v_mfma_f32_16x16x32_bf16 v[66:69], v[184:187], v[224:227], 0
	v_mfma_f32_16x16x32_bf16 v[118:121], v[180:183], v[200:203], v[118:121]
	v_mfma_f32_16x16x32_bf16 v[114:117], v[188:191], v[200:203], v[114:117]
	v_mfma_f32_16x16x32_bf16 v[102:105], v[180:183], v[208:211], v[102:105]
	v_mfma_f32_16x16x32_bf16 v[98:101], v[188:191], v[208:211], v[98:101]
	v_mfma_f32_16x16x32_bf16 v[86:89], v[180:183], v[220:223], v[86:89]
	v_mfma_f32_16x16x32_bf16 v[82:85], v[188:191], v[220:223], v[82:85]
	v_mfma_f32_16x16x32_bf16 v[70:73], v[180:183], v[228:231], v[70:73]
	v_mfma_f32_16x16x32_bf16 v[66:69], v[188:191], v[228:231], v[66:69]
	s_setprio 0
	s_waitcnt vmcnt(8)
	s_barrier
	ds_read_b128 v[196:199], v179 offset:16384
	ds_read_b128 v[200:203], v179 offset:17408
	ds_read_b128 v[204:207], v179 offset:18432
	ds_read_b128 v[208:211], v179 offset:19456
	ds_read_b128 v[212:215], v179 offset:20480
	ds_read_b128 v[220:223], v179 offset:21504
	ds_read_b128 v[224:227], v179 offset:22528
	ds_read_b128 v[228:231], v179 offset:23552
	s_add_u32 vcc_lo, s40, 0x100000
	s_addc_u32 vcc_hi, s41, 0
	s_add_i32 m0, s24, 0x10000
	s_nop 0
	global_load_lds_dwordx4 v148, s[40:41]
	s_add_i32 m0, s24, 0x12000
	s_nop 0
	global_load_lds_dwordx4 v152, s[40:41]
	s_add_i32 m0, s24, 0x14000
	s_nop 0
	global_load_lds_dwordx4 v148, vcc
	s_add_i32 m0, s24, 0x16000
	s_nop 0
	global_load_lds_dwordx4 v152, vcc
	s_mov_b32 m0, s24
	s_nop 0
	global_load_lds_dwordx4 v146, s[42:43]
	s_add_i32 m0, s24, 0x2000
	s_nop 0
	global_load_lds_dwordx4 v150, s[42:43]
	s_waitcnt lgkmcnt(0)
	s_setprio 1
	v_mfma_f32_16x16x32_bf16 v[62:65], v[130:133], v[196:199], 0
	v_mfma_f32_16x16x32_bf16 v[58:61], v[138:141], v[196:199], 0
	v_mfma_f32_16x16x32_bf16 v[46:49], v[130:133], v[204:207], 0
	v_mfma_f32_16x16x32_bf16 v[42:45], v[138:141], v[204:207], 0
	v_mfma_f32_16x16x32_bf16 v[30:33], v[130:133], v[212:215], 0
	v_mfma_f32_16x16x32_bf16 v[26:29], v[138:141], v[212:215], 0
	v_mfma_f32_16x16x32_bf16 v[14:17], v[130:133], v[224:227], 0
	v_mfma_f32_16x16x32_bf16 v[10:13], v[138:141], v[224:227], 0
	v_mfma_f32_16x16x32_bf16 v[62:65], v[134:137], v[200:203], v[62:65]
	v_mfma_f32_16x16x32_bf16 v[58:61], v[142:145], v[200:203], v[58:61]
	v_mfma_f32_16x16x32_bf16 v[46:49], v[134:137], v[208:211], v[46:49]
	v_mfma_f32_16x16x32_bf16 v[42:45], v[142:145], v[208:211], v[42:45]
	v_mfma_f32_16x16x32_bf16 v[30:33], v[134:137], v[220:223], v[30:33]
	v_mfma_f32_16x16x32_bf16 v[26:29], v[142:145], v[220:223], v[26:29]
	v_mfma_f32_16x16x32_bf16 v[14:17], v[134:137], v[228:231], v[14:17]
	v_mfma_f32_16x16x32_bf16 v[10:13], v[142:145], v[228:231], v[10:13]
	v_mfma_f32_16x16x32_bf16 v[54:57], v[162:165], v[196:199], 0
	v_mfma_f32_16x16x32_bf16 v[50:53], v[184:187], v[196:199], 0
	v_mfma_f32_16x16x32_bf16 v[38:41], v[162:165], v[204:207], 0
	v_mfma_f32_16x16x32_bf16 v[34:37], v[184:187], v[204:207], 0
	v_mfma_f32_16x16x32_bf16 v[22:25], v[162:165], v[212:215], 0
	v_mfma_f32_16x16x32_bf16 v[18:21], v[184:187], v[212:215], 0
	v_mfma_f32_16x16x32_bf16 v[6:9], v[162:165], v[224:227], 0
	v_mfma_f32_16x16x32_bf16 v[2:5], v[184:187], v[224:227], 0
	v_mfma_f32_16x16x32_bf16 v[54:57], v[180:183], v[200:203], v[54:57]
	v_mfma_f32_16x16x32_bf16 v[50:53], v[188:191], v[200:203], v[50:53]
	v_mfma_f32_16x16x32_bf16 v[38:41], v[180:183], v[208:211], v[38:41]
	v_mfma_f32_16x16x32_bf16 v[34:37], v[188:191], v[208:211], v[34:37]
	v_mfma_f32_16x16x32_bf16 v[22:25], v[180:183], v[220:223], v[22:25]
	v_mfma_f32_16x16x32_bf16 v[18:21], v[188:191], v[220:223], v[18:21]
	v_mfma_f32_16x16x32_bf16 v[6:9], v[180:183], v[228:231], v[6:9]
	v_mfma_f32_16x16x32_bf16 v[2:5], v[188:191], v[228:231], v[2:5]
	s_setprio 0
	s_waitcnt vmcnt(8)
	s_barrier
; #define PG8_STAGE(bufoff, gbase, voff) do { _Pragma("unroll") for (int _i = 0; _i < 2; ++_i) \
;         __builtin_amdgcn_global_load_lds((const unsigned*)((const char*)(gbase) + (voff)[_i]), (PG8_LAS unsigned*)(lds + (bufoff) + ldsw + _i * 8192), 16, 0, 0); } while (0)
; #define PG8_LDA(dst, b, h) do { _Pragma("unroll") for (int m = 0; m < 4; ++m) _Pragma("unroll") for (int k = 0; k < 2; ++k) dst[m][k] = *(const PG8_LAS bf16x8*)(lds + PG8_SA(b, h) + aoff + m * 2048 + k * 1024); } while (0)
; #define PG8_LDB(dst, b, h) do { _Pragma("unroll") for (int n = 0; n < 2; ++n) _Pragma("unroll") for (int k = 0; k < 2; ++k) dst[n][k] = *(const PG8_LAS bf16x8*)(lds + PG8_SB(b, h) + boff + n * 2048 + k * 1024); } while (0)
; #define PG8_MMA(ai, bj, At, Bt) do { __builtin_amdgcn_s_setprio(1); _Pragma("unroll") for (int m = 0; m < 4; ++m) _Pragma("unroll") for (int n = 0; n < 2; ++n) _Pragma("unroll") for (int k = 0; k < 2; ++k) \
;         acc[ai][bj][m][n] = __builtin_amdgcn_mfma_f32_16x16x32_bf16(Bt[n][k], At[m][k], acc[ai][bj][m][n], 0, 0, 0); __builtin_amdgcn_s_setprio(0); } while (0)
; #define PG8_BAR __builtin_amdgcn_s_barrier()
; template <class Epi, class Sched, bool ALIGN_EPI = false, bool SP2 = false>
; __device__ __forceinline__ void gemm_phase(PG8_LAS unsigned char* lds, const Gemm g, const Sched& S, const Epi& E) {
;     ...
;             if constexpr (SP2) {
;             PG8_LDB(B0, 0, 0); PG8_LDB(B1, 0, 1); PG8_SCHED; PG8_LDA(At, 0, 0); PG8_STAGE(PG8_SA(1, 1), a1 + hstep, voffA);
;             PG8_WAIT_V(8); PG8_WAIT_L(0); PG8_BAR; PG8_MMA(0, 0, At, B0); PG8_MMA(0, 1, At, B1); PG8_BAR; PG8_SCHED;
;             PG8_LDA(At, 0, 1); PG8_STAGE(PG8_SB(0, 0), b2, voffB); PG8_STAGE(PG8_SB(0, 1), b2 + hstep, voffB); PG8_STAGE(PG8_SA(0, 0), a2, voffA);
;             PG8_WAIT_V(8); PG8_WAIT_L(0); PG8_BAR; PG8_MMA(1, 0, At, B0); PG8_MMA(1, 1, At, B1); PG8_BAR; PG8_SCHED;
;             PG8_LDB(B0, 1, 0); PG8_LDB(B1, 1, 1); PG8_SCHED; PG8_LDA(At, 1, 0); PG8_STAGE(PG8_SA(0, 1), a2 + hstep, voffA);
;             PG8_WAIT_V(8); PG8_WAIT_L(0); PG8_BAR; PG8_MMA(0, 0, At, B0); PG8_MMA(0, 1, At, B1); PG8_BAR; PG8_SCHED;
;             PG8_LDA(At, 1, 1); PG8_STAGE(PG8_SB(1, 0), b3, voffB); PG8_STAGE(PG8_SB(1, 1), b3 + hstep, voffB); PG8_STAGE(PG8_SA(1, 0), a3, voffA);
;             PG8_WAIT_V(8); PG8_WAIT_L(0); PG8_BAR; PG8_MMA(1, 0, At, B0); PG8_MMA(1, 1, At, B1); PG8_BAR; PG8_SCHED;
	s_add_i32 s59, 0, 0x18000
	s_add_i32 s60, 0, 0x1c000
	v_add_u32_e32 v142, s59, v166
	v_add_u32_e32 v188, s60, v166
	ds_read_b128 v[130:133], v142
	ds_read_b128 v[134:137], v142 offset:1024
	ds_read_b128 v[138:141], v142 offset:2048
	ds_read_b128 v[142:145], v142 offset:3072
	ds_read_b128 v[162:165], v188
	ds_read_b128 v[180:183], v188 offset:1024
	ds_read_b128 v[184:187], v188 offset:2048
	ds_read_b128 v[188:191], v188 offset:3072
	ds_read_b128 v[196:199], v179 offset:32768
	ds_read_b128 v[200:203], v179 offset:33792
	ds_read_b128 v[204:207], v179 offset:34816
	ds_read_b128 v[208:211], v179 offset:35840
	ds_read_b128 v[212:215], v179 offset:36864
	ds_read_b128 v[220:223], v179 offset:37888
	ds_read_b128 v[224:227], v179 offset:38912
	ds_read_b128 v[228:231], v179 offset:39936
	s_add_u32 vcc_lo, s42, 0x100000
	s_addc_u32 vcc_hi, s43, 0
	s_add_i32 m0, s24, 0x4000
	s_nop 0
	global_load_lds_dwordx4 v146, vcc
	s_add_i32 m0, s24, 0x6000
	s_nop 0
	global_load_lds_dwordx4 v150, vcc
	s_waitcnt lgkmcnt(0)
	s_setprio 1
	v_mfma_f32_16x16x32_bf16 v[126:129], v[130:133], v[196:199], v[126:129]
	v_mfma_f32_16x16x32_bf16 v[122:125], v[138:141], v[196:199], v[122:125]
	v_mfma_f32_16x16x32_bf16 v[110:113], v[130:133], v[204:207], v[110:113]
	v_mfma_f32_16x16x32_bf16 v[106:109], v[138:141], v[204:207], v[106:109]
	v_mfma_f32_16x16x32_bf16 v[94:97], v[130:133], v[212:215], v[94:97]
	v_mfma_f32_16x16x32_bf16 v[90:93], v[138:141], v[212:215], v[90:93]
	v_mfma_f32_16x16x32_bf16 v[78:81], v[130:133], v[224:227], v[78:81]
	v_mfma_f32_16x16x32_bf16 v[74:77], v[138:141], v[224:227], v[74:77]
	v_mfma_f32_16x16x32_bf16 v[126:129], v[134:137], v[200:203], v[126:129]
	v_mfma_f32_16x16x32_bf16 v[122:125], v[142:145], v[200:203], v[122:125]
	v_mfma_f32_16x16x32_bf16 v[110:113], v[134:137], v[208:211], v[110:113]
	v_mfma_f32_16x16x32_bf16 v[106:109], v[142:145], v[208:211], v[106:109]
	v_mfma_f32_16x16x32_bf16 v[94:97], v[134:137], v[220:223], v[94:97]
	v_mfma_f32_16x16x32_bf16 v[90:93], v[142:145], v[220:223], v[90:93]
	v_mfma_f32_16x16x32_bf16 v[78:81], v[134:137], v[228:231], v[78:81]
	v_mfma_f32_16x16x32_bf16 v[74:77], v[142:145], v[228:231], v[74:77]
	v_mfma_f32_16x16x32_bf16 v[118:121], v[162:165], v[196:199], v[118:121]
	v_mfma_f32_16x16x32_bf16 v[114:117], v[184:187], v[196:199], v[114:117]
	v_mfma_f32_16x16x32_bf16 v[102:105], v[162:165], v[204:207], v[102:105]
	v_mfma_f32_16x16x32_bf16 v[98:101], v[184:187], v[204:207], v[98:101]
	v_mfma_f32_16x16x32_bf16 v[86:89], v[162:165], v[212:215], v[86:89]
	v_mfma_f32_16x16x32_bf16 v[82:85], v[184:187], v[212:215], v[82:85]
	v_mfma_f32_16x16x32_bf16 v[70:73], v[162:165], v[224:227], v[70:73]
	v_mfma_f32_16x16x32_bf16 v[66:69], v[184:187], v[224:227], v[66:69]
	v_mfma_f32_16x16x32_bf16 v[118:121], v[180:183], v[200:203], v[118:121]
	v_mfma_f32_16x16x32_bf16 v[114:117], v[188:191], v[200:203], v[114:117]
	v_mfma_f32_16x16x32_bf16 v[102:105], v[180:183], v[208:211], v[102:105]
	v_mfma_f32_16x16x32_bf16 v[98:101], v[188:191], v[208:211], v[98:101]
	v_mfma_f32_16x16x32_bf16 v[86:89], v[180:183], v[220:223], v[86:89]
	v_mfma_f32_16x16x32_bf16 v[82:85], v[188:191], v[220:223], v[82:85]
	v_mfma_f32_16x16x32_bf16 v[70:73], v[180:183], v[228:231], v[70:73]
	v_mfma_f32_16x16x32_bf16 v[66:69], v[188:191], v[228:231], v[66:69]
	s_setprio 0
	s_waitcnt vmcnt(8)
	s_barrier
	ds_read_b128 v[196:199], v179 offset:49152
	ds_read_b128 v[200:203], v179 offset:50176
	ds_read_b128 v[204:207], v179 offset:51200
	ds_read_b128 v[208:211], v179 offset:52224
	ds_read_b128 v[212:215], v179 offset:53248
	ds_read_b128 v[220:223], v179 offset:54272
	ds_read_b128 v[224:227], v179 offset:55296
	ds_read_b128 v[228:231], v179 offset:56320
	s_add_u32 s60, s40, 0x80
	s_addc_u32 s61, s41, 0
	s_add_u32 vcc_lo, s60, 0x100000
	s_addc_u32 vcc_hi, s61, 0
	s_add_i32 m0, s24, 0x18000
	s_nop 0
	global_load_lds_dwordx4 v148, s[60:61]
	s_add_i32 m0, s24, 0x1a000
	s_nop 0
	global_load_lds_dwordx4 v152, s[60:61]
	s_add_i32 m0, s24, 0x1c000
	s_nop 0
	global_load_lds_dwordx4 v148, vcc
	s_add_i32 m0, s24, 0x1e000
	s_nop 0
	global_load_lds_dwordx4 v152, vcc
	s_add_u32 s60, s42, 0x80
	s_addc_u32 s61, s43, 0
	s_add_i32 m0, s24, 0x8000
	s_nop 0
	global_load_lds_dwordx4 v146, s[60:61]
	s_add_i32 m0, s24, 0xa000
	s_nop 0
	global_load_lds_dwordx4 v150, s[60:61]
	s_waitcnt lgkmcnt(0)
	s_setprio 1
	v_mfma_f32_16x16x32_bf16 v[62:65], v[130:133], v[196:199], v[62:65]
	v_mfma_f32_16x16x32_bf16 v[58:61], v[138:141], v[196:199], v[58:61]
	v_mfma_f32_16x16x32_bf16 v[46:49], v[130:133], v[204:207], v[46:49]
	v_mfma_f32_16x16x32_bf16 v[42:45], v[138:141], v[204:207], v[42:45]
	v_mfma_f32_16x16x32_bf16 v[30:33], v[130:133], v[212:215], v[30:33]
	v_mfma_f32_16x16x32_bf16 v[26:29], v[138:141], v[212:215], v[26:29]
	v_mfma_f32_16x16x32_bf16 v[14:17], v[130:133], v[224:227], v[14:17]
	v_mfma_f32_16x16x32_bf16 v[10:13], v[138:141], v[224:227], v[10:13]
	v_mfma_f32_16x16x32_bf16 v[62:65], v[134:137], v[200:203], v[62:65]
	v_mfma_f32_16x16x32_bf16 v[58:61], v[142:145], v[200:203], v[58:61]
	v_mfma_f32_16x16x32_bf16 v[46:49], v[134:137], v[208:211], v[46:49]
	v_mfma_f32_16x16x32_bf16 v[42:45], v[142:145], v[208:211], v[42:45]
	v_mfma_f32_16x16x32_bf16 v[30:33], v[134:137], v[220:223], v[30:33]
	v_mfma_f32_16x16x32_bf16 v[26:29], v[142:145], v[220:223], v[26:29]
	v_mfma_f32_16x16x32_bf16 v[14:17], v[134:137], v[228:231], v[14:17]
	v_mfma_f32_16x16x32_bf16 v[10:13], v[142:145], v[228:231], v[10:13]
	v_mfma_f32_16x16x32_bf16 v[54:57], v[162:165], v[196:199], v[54:57]
	v_mfma_f32_16x16x32_bf16 v[50:53], v[184:187], v[196:199], v[50:53]
	v_mfma_f32_16x16x32_bf16 v[38:41], v[162:165], v[204:207], v[38:41]
	v_mfma_f32_16x16x32_bf16 v[34:37], v[184:187], v[204:207], v[34:37]
	v_mfma_f32_16x16x32_bf16 v[22:25], v[162:165], v[212:215], v[22:25]
	v_mfma_f32_16x16x32_bf16 v[18:21], v[184:187], v[212:215], v[18:21]
	v_mfma_f32_16x16x32_bf16 v[6:9], v[162:165], v[224:227], v[6:9]
	v_mfma_f32_16x16x32_bf16 v[2:5], v[184:187], v[224:227], v[2:5]
	v_mfma_f32_16x16x32_bf16 v[54:57], v[180:183], v[200:203], v[54:57]
	v_mfma_f32_16x16x32_bf16 v[50:53], v[188:191], v[200:203], v[50:53]
	v_mfma_f32_16x16x32_bf16 v[38:41], v[180:183], v[208:211], v[38:41]
	v_mfma_f32_16x16x32_bf16 v[34:37], v[188:191], v[208:211], v[34:37]
	v_mfma_f32_16x16x32_bf16 v[22:25], v[180:183], v[220:223], v[22:25]
	v_mfma_f32_16x16x32_bf16 v[18:21], v[188:191], v[220:223], v[18:21]
	v_mfma_f32_16x16x32_bf16 v[6:9], v[180:183], v[228:231], v[6:9]
	v_mfma_f32_16x16x32_bf16 v[2:5], v[188:191], v[228:231], v[2:5]
	s_setprio 0
	s_waitcnt vmcnt(8)
	s_barrier
	s_add_i32 s58, s58, 2
	s_add_u32 s36, s36, 0x100
	s_addc_u32 s37, s37, 0
	s_add_u32 s56, s56, 0x100
	s_addc_u32 s57, s57, 0
	s_cmp_gt_u32 s58, 61

; #define PG8_STAGE(bufoff, gbase, voff) do { _Pragma("unroll") for (int _i = 0; _i < 2; ++_i) \
;         __builtin_amdgcn_global_load_lds((const unsigned*)((const char*)(gbase) + (voff)[_i]), (PG8_LAS unsigned*)(lds + (bufoff) + ldsw + _i * 8192), 16, 0, 0); } while (0)
; #define PG8_LDA(dst, b, h) do { _Pragma("unroll") for (int m = 0; m < 4; ++m) _Pragma("unroll") for (int k = 0; k < 2; ++k) dst[m][k] = *(const PG8_LAS bf16x8*)(lds + PG8_SA(b, h) + aoff + m * 2048 + k * 1024); } while (0)
; #define PG8_LDB(dst, b, h) do { _Pragma("unroll") for (int n = 0; n < 2; ++n) _Pragma("unroll") for (int k = 0; k < 2; ++k) dst[n][k] = *(const PG8_LAS bf16x8*)(lds + PG8_SB(b, h) + boff + n * 2048 + k * 1024); } while (0)
; #define PG8_MMA(ai, bj, At, Bt) do { __builtin_amdgcn_s_setprio(1); _Pragma("unroll") for (int m = 0; m < 4; ++m) _Pragma("unroll") for (int n = 0; n < 2; ++n) _Pragma("unroll") for (int k = 0; k < 2; ++k) \
;         acc[ai][bj][m][n] = __builtin_amdgcn_mfma_f32_16x16x32_bf16(Bt[n][k], At[m][k], acc[ai][bj][m][n], 0, 0, 0); __builtin_amdgcn_s_setprio(0); } while (0)
; #define PG8_BAR __builtin_amdgcn_s_barrier()
; template <class Epi, class Sched, bool ALIGN_EPI = false, bool SP2 = false>
; __device__ __forceinline__ void gemm_phase(PG8_LAS unsigned char* lds, const Gemm g, const Sched& S, const Epi& E) {
;     ...
;             if constexpr (SP2) {
;             PG8_LDB(B0, 0, 0); PG8_LDB(B1, 0, 1); PG8_SCHED; PG8_LDA(At, 0, 0); PG8_STAGE(PG8_SA(1, 1), a1 + hstep, voffA);
;             PG8_WAIT_V(8); PG8_WAIT_L(0); PG8_BAR; PG8_MMA(0, 0, At, B0); PG8_MMA(0, 1, At, B1); PG8_BAR; PG8_SCHED;
;             PG8_LDA(At, 0, 1); PG8_STAGE(PG8_SB(0, 0), b2, voffB); PG8_STAGE(PG8_SB(0, 1), b2 + hstep, voffB); PG8_STAGE(PG8_SA(0, 0), a2, voffA);
;             PG8_WAIT_V(8); PG8_WAIT_L(0); PG8_BAR; PG8_MMA(1, 0, At, B0); PG8_MMA(1, 1, At, B1); PG8_BAR; PG8_SCHED;
;             PG8_LDB(B0, 1, 0); PG8_LDB(B1, 1, 1); PG8_SCHED; PG8_LDA(At, 1, 0); PG8_STAGE(PG8_SA(0, 1), a2 + hstep, voffA);
;             PG8_WAIT_V(8); PG8_WAIT_L(0); PG8_BAR; PG8_MMA(0, 0, At, B0); PG8_MMA(0, 1, At, B1); PG8_BAR; PG8_SCHED;
;             PG8_LDA(At, 1, 1); PG8_STAGE(PG8_SB(1, 0), b3, voffB); PG8_STAGE(PG8_SB(1, 1), b3 + hstep, voffB); PG8_STAGE(PG8_SA(1, 0), a3, voffA);
;             PG8_WAIT_V(8); PG8_WAIT_L(0); PG8_BAR; PG8_MMA(1, 0, At, B0); PG8_MMA(1, 1, At, B1); PG8_BAR; PG8_SCHED;
.Lf1_h1first:
	ds_read_b128 v[130:133], v177
	ds_read_b128 v[134:137], v177 offset:1024
	ds_read_b128 v[138:141], v177 offset:2048
	ds_read_b128 v[142:145], v177 offset:3072
	ds_read_b128 v[162:165], v178
	ds_read_b128 v[180:183], v178 offset:1024
	ds_read_b128 v[184:187], v178 offset:2048
	ds_read_b128 v[188:191], v178 offset:3072
	s_add_u32 s40, s36, 0xfff00080
	s_addc_u32 s41, s37, -1
	s_cmp_eq_u32 s58, 60
	s_cselect_b32 s43, s15, s41
	s_cselect_b32 s42, s17, s40
	s_cselect_b32 s41, s54, s57
	s_cselect_b32 s40, s55, s56
	ds_read_b128 v[196:199], v179
	ds_read_b128 v[200:203], v179 offset:1024
	ds_read_b128 v[204:207], v179 offset:2048
	ds_read_b128 v[208:211], v179 offset:3072
	ds_read_b128 v[212:215], v179 offset:4096
	ds_read_b128 v[220:223], v179 offset:5120
	ds_read_b128 v[224:227], v179 offset:6144
	ds_read_b128 v[228:231], v179 offset:7168
	s_add_i32 m0, s24, 0xc000
	s_nop 0
	global_load_lds_dwordx4 v146, s[36:37]
	s_add_i32 m0, s24, 0xe000
	s_nop 0
	global_load_lds_dwordx4 v150, s[36:37]
	s_sleep 2
	s_waitcnt lgkmcnt(0)
	s_waitcnt vmcnt(8)
	s_barrier
	s_setprio 2
	v_mfma_f32_16x16x32_bf16 v[126:129], v[130:133], v[196:199], 0
	v_mfma_f32_16x16x32_bf16 v[122:125], v[138:141], v[196:199], 0
	v_mfma_f32_16x16x32_bf16 v[110:113], v[130:133], v[204:207], 0
	v_mfma_f32_16x16x32_bf16 v[106:109], v[138:141], v[204:207], 0
	v_mfma_f32_16x16x32_bf16 v[94:97], v[130:133], v[212:215], 0
	v_mfma_f32_16x16x32_bf16 v[90:93], v[138:141], v[212:215], 0
	v_mfma_f32_16x16x32_bf16 v[78:81], v[130:133], v[224:227], 0
	v_mfma_f32_16x16x32_bf16 v[74:77], v[138:141], v[224:227], 0
	v_mfma_f32_16x16x32_bf16 v[126:129], v[134:137], v[200:203], v[126:129]
	v_mfma_f32_16x16x32_bf16 v[122:125], v[142:145], v[200:203], v[122:125]
	v_mfma_f32_16x16x32_bf16 v[110:113], v[134:137], v[208:211], v[110:113]
	v_mfma_f32_16x16x32_bf16 v[106:109], v[142:145], v[208:211], v[106:109]
	v_mfma_f32_16x16x32_bf16 v[94:97], v[134:137], v[220:223], v[94:97]
	v_mfma_f32_16x16x32_bf16 v[90:93], v[142:145], v[220:223], v[90:93]
	v_mfma_f32_16x16x32_bf16 v[78:81], v[134:137], v[228:231], v[78:81]
	v_mfma_f32_16x16x32_bf16 v[74:77], v[142:145], v[228:231], v[74:77]
	v_mfma_f32_16x16x32_bf16 v[118:121], v[162:165], v[196:199], 0
	v_mfma_f32_16x16x32_bf16 v[114:117], v[184:187], v[196:199], 0
	v_mfma_f32_16x16x32_bf16 v[102:105], v[162:165], v[204:207], 0
	v_mfma_f32_16x16x32_bf16 v[98:101], v[184:187], v[204:207], 0
	v_mfma_f32_16x16x32_bf16 v[86:89], v[162:165], v[212:215], 0
	v_mfma_f32_16x16x32_bf16 v[82:85], v[184:187], v[212:215], 0
	v_mfma_f32_16x16x32_bf16 v[70:73], v[162:165], v[224:227], 0
	v_mfma_f32_16x16x32_bf16 v[66:69], v[184:187], v[224:227], 0
	v_mfma_f32_16x16x32_bf16 v[118:121], v[180:183], v[200:203], v[118:121]
	v_mfma_f32_16x16x32_bf16 v[114:117], v[188:191], v[200:203], v[114:117]
	v_mfma_f32_16x16x32_bf16 v[102:105], v[180:183], v[208:211], v[102:105]
	v_mfma_f32_16x16x32_bf16 v[98:101], v[188:191], v[208:211], v[98:101]
	v_mfma_f32_16x16x32_bf16 v[86:89], v[180:183], v[220:223], v[86:89]
	v_mfma_f32_16x16x32_bf16 v[82:85], v[188:191], v[220:223], v[82:85]
	v_mfma_f32_16x16x32_bf16 v[70:73], v[180:183], v[228:231], v[70:73]
	v_mfma_f32_16x16x32_bf16 v[66:69], v[188:191], v[228:231], v[66:69]
	s_setprio 0
	ds_read_b128 v[196:199], v179 offset:16384
	ds_read_b128 v[200:203], v179 offset:17408
	ds_read_b128 v[204:207], v179 offset:18432
	ds_read_b128 v[208:211], v179 offset:19456
	ds_read_b128 v[212:215], v179 offset:20480
	ds_read_b128 v[220:223], v179 offset:21504
	ds_read_b128 v[224:227], v179 offset:22528
	ds_read_b128 v[228:231], v179 offset:23552
	s_add_u32 vcc_lo, s40, 0x100000
	s_addc_u32 vcc_hi, s41, 0
	s_add_i32 m0, s24, 0x10000
	s_nop 0
	global_load_lds_dwordx4 v148, s[40:41]
	s_add_i32 m0, s24, 0x12000
	s_nop 0
	global_load_lds_dwordx4 v152, s[40:41]
	s_add_i32 m0, s24, 0x14000
	s_nop 0
	global_load_lds_dwordx4 v148, vcc
	s_add_i32 m0, s24, 0x16000
	s_nop 0
	global_load_lds_dwordx4 v152, vcc
	s_mov_b32 m0, s24
	s_nop 0
	global_load_lds_dwordx4 v146, s[42:43]
	s_add_i32 m0, s24, 0x2000
	s_nop 0
	global_load_lds_dwordx4 v150, s[42:43]
	s_sleep 2
	s_waitcnt lgkmcnt(0)
	s_waitcnt vmcnt(8)
	s_barrier
	s_setprio 2
	v_mfma_f32_16x16x32_bf16 v[62:65], v[130:133], v[196:199], 0
	v_mfma_f32_16x16x32_bf16 v[58:61], v[138:141], v[196:199], 0
	v_mfma_f32_16x16x32_bf16 v[46:49], v[130:133], v[204:207], 0
	v_mfma_f32_16x16x32_bf16 v[42:45], v[138:141], v[204:207], 0
	v_mfma_f32_16x16x32_bf16 v[30:33], v[130:133], v[212:215], 0
	v_mfma_f32_16x16x32_bf16 v[26:29], v[138:141], v[212:215], 0
	v_mfma_f32_16x16x32_bf16 v[14:17], v[130:133], v[224:227], 0
	v_mfma_f32_16x16x32_bf16 v[10:13], v[138:141], v[224:227], 0
	v_mfma_f32_16x16x32_bf16 v[62:65], v[134:137], v[200:203], v[62:65]
	v_mfma_f32_16x16x32_bf16 v[58:61], v[142:145], v[200:203], v[58:61]
	v_mfma_f32_16x16x32_bf16 v[46:49], v[134:137], v[208:211], v[46:49]
	v_mfma_f32_16x16x32_bf16 v[42:45], v[142:145], v[208:211], v[42:45]
	v_mfma_f32_16x16x32_bf16 v[30:33], v[134:137], v[220:223], v[30:33]
	v_mfma_f32_16x16x32_bf16 v[26:29], v[142:145], v[220:223], v[26:29]
	v_mfma_f32_16x16x32_bf16 v[14:17], v[134:137], v[228:231], v[14:17]
	v_mfma_f32_16x16x32_bf16 v[10:13], v[142:145], v[228:231], v[10:13]
	v_mfma_f32_16x16x32_bf16 v[54:57], v[162:165], v[196:199], 0
	v_mfma_f32_16x16x32_bf16 v[50:53], v[184:187], v[196:199], 0
	v_mfma_f32_16x16x32_bf16 v[38:41], v[162:165], v[204:207], 0
	v_mfma_f32_16x16x32_bf16 v[34:37], v[184:187], v[204:207], 0
	v_mfma_f32_16x16x32_bf16 v[22:25], v[162:165], v[212:215], 0
	v_mfma_f32_16x16x32_bf16 v[18:21], v[184:187], v[212:215], 0
	v_mfma_f32_16x16x32_bf16 v[6:9], v[162:165], v[224:227], 0
; #define PG8_STAGE(bufoff, gbase, voff) do { _Pragma("unroll") for (int _i = 0; _i < 2; ++_i) \
;         __builtin_amdgcn_global_load_lds((const unsigned*)((const char*)(gbase) + (voff)[_i]), (PG8_LAS unsigned*)(lds + (bufoff) + ldsw + _i * 8192), 16, 0, 0); } while (0)
; #define PG8_LDA(dst, b, h) do { _Pragma("unroll") for (int m = 0; m < 4; ++m) _Pragma("unroll") for (int k = 0; k < 2; ++k) dst[m][k] = *(const PG8_LAS bf16x8*)(lds + PG8_SA(b, h) + aoff + m * 2048 + k * 1024); } while (0)
; #define PG8_LDB(dst, b, h) do { _Pragma("unroll") for (int n = 0; n < 2; ++n) _Pragma("unroll") for (int k = 0; k < 2; ++k) dst[n][k] = *(const PG8_LAS bf16x8*)(lds + PG8_SB(b, h) + boff + n * 2048 + k * 1024); } while (0)
; #define PG8_MMA(ai, bj, At, Bt) do { __builtin_amdgcn_s_setprio(1); _Pragma("unroll") for (int m = 0; m < 4; ++m) _Pragma("unroll") for (int n = 0; n < 2; ++n) _Pragma("unroll") for (int k = 0; k < 2; ++k) \
;         acc[ai][bj][m][n] = __builtin_amdgcn_mfma_f32_16x16x32_bf16(Bt[n][k], At[m][k], acc[ai][bj][m][n], 0, 0, 0); __builtin_amdgcn_s_setprio(0); } while (0)
; #define PG8_BAR __builtin_amdgcn_s_barrier()
; template <class Epi, class Sched, bool ALIGN_EPI = false, bool SP2 = false>
; __device__ __forceinline__ void gemm_phase(PG8_LAS unsigned char* lds, const Gemm g, const Sched& S, const Epi& E) {
;     ...
;             if constexpr (SP2) {
;             PG8_LDB(B0, 0, 0); PG8_LDB(B1, 0, 1); PG8_SCHED; PG8_LDA(At, 0, 0); PG8_STAGE(PG8_SA(1, 1), a1 + hstep, voffA);
;             PG8_WAIT_V(8); PG8_WAIT_L(0); PG8_BAR; PG8_MMA(0, 0, At, B0); PG8_MMA(0, 1, At, B1); PG8_BAR; PG8_SCHED;
;             PG8_LDA(At, 0, 1); PG8_STAGE(PG8_SB(0, 0), b2, voffB); PG8_STAGE(PG8_SB(0, 1), b2 + hstep, voffB); PG8_STAGE(PG8_SA(0, 0), a2, voffA);
;             PG8_WAIT_V(8); PG8_WAIT_L(0); PG8_BAR; PG8_MMA(1, 0, At, B0); PG8_MMA(1, 1, At, B1); PG8_BAR; PG8_SCHED;
;             PG8_LDB(B0, 1, 0); PG8_LDB(B1, 1, 1); PG8_SCHED; PG8_LDA(At, 1, 0); PG8_STAGE(PG8_SA(0, 1), a2 + hstep, voffA);
;             PG8_WAIT_V(8); PG8_WAIT_L(0); PG8_BAR; PG8_MMA(0, 0, At, B0); PG8_MMA(0, 1, At, B1); PG8_BAR; PG8_SCHED;
;             PG8_LDA(At, 1, 1); PG8_STAGE(PG8_SB(1, 0), b3, voffB); PG8_STAGE(PG8_SB(1, 1), b3 + hstep, voffB); PG8_STAGE(PG8_SA(1, 0), a3, voffA);
;             PG8_WAIT_V(8); PG8_WAIT_L(0); PG8_BAR; PG8_MMA(1, 0, At, B0); PG8_MMA(1, 1, At, B1); PG8_BAR; PG8_SCHED;
	v_mfma_f32_16x16x32_bf16 v[2:5], v[184:187], v[224:227], 0
	v_mfma_f32_16x16x32_bf16 v[54:57], v[180:183], v[200:203], v[54:57]
	v_mfma_f32_16x16x32_bf16 v[50:53], v[188:191], v[200:203], v[50:53]
	v_mfma_f32_16x16x32_bf16 v[38:41], v[180:183], v[208:211], v[38:41]
	v_mfma_f32_16x16x32_bf16 v[34:37], v[188:191], v[208:211], v[34:37]
	v_mfma_f32_16x16x32_bf16 v[22:25], v[180:183], v[220:223], v[22:25]
	v_mfma_f32_16x16x32_bf16 v[18:21], v[188:191], v[220:223], v[18:21]
	v_mfma_f32_16x16x32_bf16 v[6:9], v[180:183], v[228:231], v[6:9]
	v_mfma_f32_16x16x32_bf16 v[2:5], v[188:191], v[228:231], v[2:5]
	s_setprio 0
	s_add_i32 s59, 0, 0x18000
	s_add_i32 s60, 0, 0x1c000
	v_add_u32_e32 v142, s59, v166
	v_add_u32_e32 v188, s60, v166
	ds_read_b128 v[130:133], v142
	ds_read_b128 v[134:137], v142 offset:1024
	ds_read_b128 v[138:141], v142 offset:2048
	ds_read_b128 v[142:145], v142 offset:3072
	ds_read_b128 v[162:165], v188
	ds_read_b128 v[180:183], v188 offset:1024
	ds_read_b128 v[184:187], v188 offset:2048
	ds_read_b128 v[188:191], v188 offset:3072
	ds_read_b128 v[196:199], v179 offset:32768
	ds_read_b128 v[200:203], v179 offset:33792
	ds_read_b128 v[204:207], v179 offset:34816
	ds_read_b128 v[208:211], v179 offset:35840
	ds_read_b128 v[212:215], v179 offset:36864
	ds_read_b128 v[220:223], v179 offset:37888
	ds_read_b128 v[224:227], v179 offset:38912
	ds_read_b128 v[228:231], v179 offset:39936
	s_add_u32 vcc_lo, s42, 0x100000
	s_addc_u32 vcc_hi, s43, 0
	s_add_i32 m0, s24, 0x4000
	s_nop 0
	global_load_lds_dwordx4 v146, vcc
	s_add_i32 m0, s24, 0x6000
	s_nop 0
	global_load_lds_dwordx4 v150, vcc
	s_sleep 2
	s_waitcnt lgkmcnt(0)
	s_waitcnt vmcnt(8)
	s_barrier
	s_setprio 2
	v_mfma_f32_16x16x32_bf16 v[126:129], v[130:133], v[196:199], v[126:129]
	v_mfma_f32_16x16x32_bf16 v[122:125], v[138:141], v[196:199], v[122:125]
	v_mfma_f32_16x16x32_bf16 v[110:113], v[130:133], v[204:207], v[110:113]
	v_mfma_f32_16x16x32_bf16 v[106:109], v[138:141], v[204:207], v[106:109]
	v_mfma_f32_16x16x32_bf16 v[94:97], v[130:133], v[212:215], v[94:97]
	v_mfma_f32_16x16x32_bf16 v[90:93], v[138:141], v[212:215], v[90:93]
	v_mfma_f32_16x16x32_bf16 v[78:81], v[130:133], v[224:227], v[78:81]
	v_mfma_f32_16x16x32_bf16 v[74:77], v[138:141], v[224:227], v[74:77]
	v_mfma_f32_16x16x32_bf16 v[126:129], v[134:137], v[200:203], v[126:129]
	v_mfma_f32_16x16x32_bf16 v[122:125], v[142:145], v[200:203], v[122:125]
	v_mfma_f32_16x16x32_bf16 v[110:113], v[134:137], v[208:211], v[110:113]
	v_mfma_f32_16x16x32_bf16 v[106:109], v[142:145], v[208:211], v[106:109]
	v_mfma_f32_16x16x32_bf16 v[94:97], v[134:137], v[220:223], v[94:97]
	v_mfma_f32_16x16x32_bf16 v[90:93], v[142:145], v[220:223], v[90:93]
	v_mfma_f32_16x16x32_bf16 v[78:81], v[134:137], v[228:231], v[78:81]
	v_mfma_f32_16x16x32_bf16 v[74:77], v[142:145], v[228:231], v[74:77]
	v_mfma_f32_16x16x32_bf16 v[118:121], v[162:165], v[196:199], v[118:121]
	v_mfma_f32_16x16x32_bf16 v[114:117], v[184:187], v[196:199], v[114:117]
	v_mfma_f32_16x16x32_bf16 v[102:105], v[162:165], v[204:207], v[102:105]
	v_mfma_f32_16x16x32_bf16 v[98:101], v[184:187], v[204:207], v[98:101]
	v_mfma_f32_16x16x32_bf16 v[86:89], v[162:165], v[212:215], v[86:89]
	v_mfma_f32_16x16x32_bf16 v[82:85], v[184:187], v[212:215], v[82:85]
	v_mfma_f32_16x16x32_bf16 v[70:73], v[162:165], v[224:227], v[70:73]
	v_mfma_f32_16x16x32_bf16 v[66:69], v[184:187], v[224:227], v[66:69]
	v_mfma_f32_16x16x32_bf16 v[118:121], v[180:183], v[200:203], v[118:121]
	v_mfma_f32_16x16x32_bf16 v[114:117], v[188:191], v[200:203], v[114:117]
	v_mfma_f32_16x16x32_bf16 v[102:105], v[180:183], v[208:211], v[102:105]
	v_mfma_f32_16x16x32_bf16 v[98:101], v[188:191], v[208:211], v[98:101]
	v_mfma_f32_16x16x32_bf16 v[86:89], v[180:183], v[220:223], v[86:89]
	v_mfma_f32_16x16x32_bf16 v[82:85], v[188:191], v[220:223], v[82:85]
	v_mfma_f32_16x16x32_bf16 v[70:73], v[180:183], v[228:231], v[70:73]
	v_mfma_f32_16x16x32_bf16 v[66:69], v[188:191], v[228:231], v[66:69]
	s_setprio 0
	ds_read_b128 v[196:199], v179 offset:49152
	ds_read_b128 v[200:203], v179 offset:50176
	ds_read_b128 v[204:207], v179 offset:51200
	ds_read_b128 v[208:211], v179 offset:52224
	ds_read_b128 v[212:215], v179 offset:53248
	ds_read_b128 v[220:223], v179 offset:54272
	ds_read_b128 v[224:227], v179 offset:55296
	ds_read_b128 v[228:231], v179 offset:56320
	s_add_u32 s60, s40, 0x80
	s_addc_u32 s61, s41, 0
	s_add_u32 vcc_lo, s60, 0x100000
	s_addc_u32 vcc_hi, s61, 0
	s_add_i32 m0, s24, 0x18000
	s_nop 0
	global_load_lds_dwordx4 v148, s[60:61]
	s_add_i32 m0, s24, 0x1a000
	s_nop 0
	global_load_lds_dwordx4 v152, s[60:61]
	s_add_i32 m0, s24, 0x1c000
	s_nop 0
	global_load_lds_dwordx4 v148, vcc
	s_add_i32 m0, s24, 0x1e000
	s_nop 0
	global_load_lds_dwordx4 v152, vcc
	s_add_u32 s60, s42, 0x80
	s_addc_u32 s61, s43, 0
	s_add_i32 m0, s24, 0x8000
	s_nop 0
	global_load_lds_dwordx4 v146, s[60:61]
	s_add_i32 m0, s24, 0xa000
	s_nop 0
	global_load_lds_dwordx4 v150, s[60:61]
	s_sleep 2
	s_waitcnt lgkmcnt(0)
	s_waitcnt vmcnt(8)
	s_barrier
; #define PG8_STAGE(bufoff, gbase, voff) do { _Pragma("unroll") for (int _i = 0; _i < 2; ++_i) \
;         __builtin_amdgcn_global_load_lds((const unsigned*)((const char*)(gbase) + (voff)[_i]), (PG8_LAS unsigned*)(lds + (bufoff) + ldsw + _i * 8192), 16, 0, 0); } while (0)
; #define PG8_LDA(dst, b, h) do { _Pragma("unroll") for (int m = 0; m < 4; ++m) _Pragma("unroll") for (int k = 0; k < 2; ++k) dst[m][k] = *(const PG8_LAS bf16x8*)(lds + PG8_SA(b, h) + aoff + m * 2048 + k * 1024); } while (0)
; #define PG8_LDB(dst, b, h) do { _Pragma("unroll") for (int n = 0; n < 2; ++n) _Pragma("unroll") for (int k = 0; k < 2; ++k) dst[n][k] = *(const PG8_LAS bf16x8*)(lds + PG8_SB(b, h) + boff + n * 2048 + k * 1024); } while (0)
; #define PG8_MMA(ai, bj, At, Bt) do { __builtin_amdgcn_s_setprio(1); _Pragma("unroll") for (int m = 0; m < 4; ++m) _Pragma("unroll") for (int n = 0; n < 2; ++n) _Pragma("unroll") for (int k = 0; k < 2; ++k) \
;         acc[ai][bj][m][n] = __builtin_amdgcn_mfma_f32_16x16x32_bf16(Bt[n][k], At[m][k], acc[ai][bj][m][n], 0, 0, 0); __builtin_amdgcn_s_setprio(0); } while (0)
; #define PG8_BAR __builtin_amdgcn_s_barrier()
; template <class Epi, class Sched, bool ALIGN_EPI = false, bool SP2 = false>
; __device__ __forceinline__ void gemm_phase(PG8_LAS unsigned char* lds, const Gemm g, const Sched& S, const Epi& E) {
;     ...
;             if constexpr (SP2) {
;             PG8_LDB(B0, 0, 0); PG8_LDB(B1, 0, 1); PG8_SCHED; PG8_LDA(At, 0, 0); PG8_STAGE(PG8_SA(1, 1), a1 + hstep, voffA);
;             PG8_WAIT_V(8); PG8_WAIT_L(0); PG8_BAR; PG8_MMA(0, 0, At, B0); PG8_MMA(0, 1, At, B1); PG8_BAR; PG8_SCHED;
;             PG8_LDA(At, 0, 1); PG8_STAGE(PG8_SB(0, 0), b2, voffB); PG8_STAGE(PG8_SB(0, 1), b2 + hstep, voffB); PG8_STAGE(PG8_SA(0, 0), a2, voffA);
;             PG8_WAIT_V(8); PG8_WAIT_L(0); PG8_BAR; PG8_MMA(1, 0, At, B0); PG8_MMA(1, 1, At, B1); PG8_BAR; PG8_SCHED;
;             PG8_LDB(B0, 1, 0); PG8_LDB(B1, 1, 1); PG8_SCHED; PG8_LDA(At, 1, 0); PG8_STAGE(PG8_SA(0, 1), a2 + hstep, voffA);
;             PG8_WAIT_V(8); PG8_WAIT_L(0); PG8_BAR; PG8_MMA(0, 0, At, B0); PG8_MMA(0, 1, At, B1); PG8_BAR; PG8_SCHED;
;             PG8_LDA(At, 1, 1); PG8_STAGE(PG8_SB(1, 0), b3, voffB); PG8_STAGE(PG8_SB(1, 1), b3 + hstep, voffB); PG8_STAGE(PG8_SA(1, 0), a3, voffA);
;             PG8_WAIT_V(8); PG8_WAIT_L(0); PG8_BAR; PG8_MMA(1, 0, At, B0); PG8_MMA(1, 1, At, B1); PG8_BAR; PG8_SCHED;
	s_setprio 2
	v_mfma_f32_16x16x32_bf16 v[62:65], v[130:133], v[196:199], v[62:65]
	v_mfma_f32_16x16x32_bf16 v[58:61], v[138:141], v[196:199], v[58:61]
	v_mfma_f32_16x16x32_bf16 v[46:49], v[130:133], v[204:207], v[46:49]
	v_mfma_f32_16x16x32_bf16 v[42:45], v[138:141], v[204:207], v[42:45]
	v_mfma_f32_16x16x32_bf16 v[30:33], v[130:133], v[212:215], v[30:33]
	v_mfma_f32_16x16x32_bf16 v[26:29], v[138:141], v[212:215], v[26:29]
	v_mfma_f32_16x16x32_bf16 v[14:17], v[130:133], v[224:227], v[14:17]
	v_mfma_f32_16x16x32_bf16 v[10:13], v[138:141], v[224:227], v[10:13]
	v_mfma_f32_16x16x32_bf16 v[62:65], v[134:137], v[200:203], v[62:65]
	v_mfma_f32_16x16x32_bf16 v[58:61], v[142:145], v[200:203], v[58:61]
	v_mfma_f32_16x16x32_bf16 v[46:49], v[134:137], v[208:211], v[46:49]
	v_mfma_f32_16x16x32_bf16 v[42:45], v[142:145], v[208:211], v[42:45]
	v_mfma_f32_16x16x32_bf16 v[30:33], v[134:137], v[220:223], v[30:33]
	v_mfma_f32_16x16x32_bf16 v[26:29], v[142:145], v[220:223], v[26:29]
	v_mfma_f32_16x16x32_bf16 v[14:17], v[134:137], v[228:231], v[14:17]
	v_mfma_f32_16x16x32_bf16 v[10:13], v[142:145], v[228:231], v[10:13]
	v_mfma_f32_16x16x32_bf16 v[54:57], v[162:165], v[196:199], v[54:57]
	v_mfma_f32_16x16x32_bf16 v[50:53], v[184:187], v[196:199], v[50:53]
	v_mfma_f32_16x16x32_bf16 v[38:41], v[162:165], v[204:207], v[38:41]
	v_mfma_f32_16x16x32_bf16 v[34:37], v[184:187], v[204:207], v[34:37]
	v_mfma_f32_16x16x32_bf16 v[22:25], v[162:165], v[212:215], v[22:25]
	v_mfma_f32_16x16x32_bf16 v[18:21], v[184:187], v[212:215], v[18:21]
	v_mfma_f32_16x16x32_bf16 v[6:9], v[162:165], v[224:227], v[6:9]
	v_mfma_f32_16x16x32_bf16 v[2:5], v[184:187], v[224:227], v[2:5]
	v_mfma_f32_16x16x32_bf16 v[54:57], v[180:183], v[200:203], v[54:57]
	v_mfma_f32_16x16x32_bf16 v[50:53], v[188:191], v[200:203], v[50:53]
	v_mfma_f32_16x16x32_bf16 v[38:41], v[180:183], v[208:211], v[38:41]
	v_mfma_f32_16x16x32_bf16 v[34:37], v[188:191], v[208:211], v[34:37]
	v_mfma_f32_16x16x32_bf16 v[22:25], v[180:183], v[220:223], v[22:25]
	v_mfma_f32_16x16x32_bf16 v[18:21], v[188:191], v[220:223], v[18:21]
	v_mfma_f32_16x16x32_bf16 v[6:9], v[180:183], v[228:231], v[6:9]
	v_mfma_f32_16x16x32_bf16 v[2:5], v[188:191], v[228:231], v[2:5]
	s_setprio 0
	s_add_i32 s58, s58, 2
	s_add_u32 s36, s36, 0x100
	s_addc_u32 s37, s37, 0
	s_add_u32 s56, s56, 0x100
	s_addc_u32 s57, s57, 0
	s_cmp_gt_u32 s58, 61

;     __device__ __forceinline__ bool next(int i, Unit& u) const { const long L = (long)i * G + c; if (L >= nwg) return false; std_map((int)L, nM, nN, u, wgm); u.ui = i; return true; }
;     __device__ __forceinline__ bool next(int i, Unit& u) const { if (i >= 4) return false; const int x = c & 7, r = c >> 3; u.pm = 16 * i + 4 * (x >> 1) + (r & 3); u.pn = 8 * (x & 1) + (r >> 2); u.ui = i; return true; }
; #define PG8_LDA(dst, b, h) do { _Pragma("unroll") for (int m = 0; m < 4; ++m) _Pragma("unroll") for (int k = 0; k < 2; ++k) dst[m][k] = *(const PG8_LAS bf16x8*)(lds + PG8_SA(b, h) + aoff + m * 2048 + k * 1024); } while (0)
; template <class Epi, class Sched, bool ALIGN_EPI = false, bool SP2 = false>
; __device__ __forceinline__ void gemm_phase(PG8_LAS unsigned char* lds, const Gemm g, const Sched& S, const Epi& E) {
;     ...
;         const bool has_next = S.next(ui + 1, nxt);
;         const char* nA = cA; const char* nB = cB; if (has_next) S.bases(nxt, g, tstep, nA, nB);
;     ...
;             if constexpr (SP2) {
;             PG8_LDB(B0, 0, 0); PG8_LDB(B1, 0, 1); PG8_SCHED; PG8_LDA(At, 0, 0); PG8_STAGE(PG8_SA(1, 1), a1 + hstep, voffA);
;             PG8_WAIT_V(8); PG8_WAIT_L(0); PG8_BAR; PG8_MMA(0, 0, At, B0); PG8_MMA(0, 1, At, B1); PG8_BAR; PG8_SCHED;
;             PG8_LDA(At, 0, 1); PG8_STAGE(PG8_SB(0, 0), b2, voffB); PG8_STAGE(PG8_SB(0, 1), b2 + hstep, voffB); PG8_STAGE(PG8_SA(0, 0), a2, voffA);
;             PG8_WAIT_V(8); PG8_WAIT_L(0); PG8_BAR; PG8_MMA(1, 0, At, B0); PG8_MMA(1, 1, At, B1); PG8_BAR; PG8_SCHED;
;             PG8_LDB(B0, 1, 0); PG8_LDB(B1, 1, 1); PG8_SCHED; PG8_LDA(At, 1, 0); PG8_STAGE(PG8_SA(0, 1), a2 + hstep, voffA);
;             PG8_WAIT_V(8); PG8_WAIT_L(0); PG8_BAR; PG8_MMA(0, 0, At, B0); PG8_MMA(0, 1, At, B1); PG8_BAR; PG8_SCHED;
;             PG8_LDA(At, 1, 1); PG8_STAGE(PG8_SB(1, 0), b3, voffB); PG8_STAGE(PG8_SB(1, 1), b3 + hstep, voffB); PG8_STAGE(PG8_SA(1, 0), a3, voffA);
;             PG8_WAIT_V(8); PG8_WAIT_L(0); PG8_BAR; PG8_MMA(1, 0, At, B0); PG8_MMA(1, 1, At, B1); PG8_BAR; PG8_SCHED;
;     ...
; #pragma unroll
;         for (int a = 0; a < 2; ++a)
; #pragma unroll
;             for (int b = 0; b < 2; ++b)
; #pragma unroll
;                 for (int m = 0; m < 4; ++m)
; #pragma unroll
;                     for (int n = 0; n < 2; ++n) acc[a][b][m][n] = (f32x4){0.f, 0.f, 0.f, 0.f};
;         cur = nxt; cA = nA; cB = nB; ++ui;
.LBB0_1320:
	s_mov_b32 s55, s28
	s_add_i32 s28, s28, 1
	s_mov_b64 s[18:19], s[6:7]
	s_lshl_b32 s6, s28, 4
	s_mov_b32 s56, s54
	s_or_b32 s54, s6, s2
	s_mul_i32 s6, s54, 0x808000
	s_add_u32 s6, s44, s6
	s_addc_u32 s7, s45, 0
	s_cmp_lt_u32 s55, 3
	s_mov_b64 s[20:21], s[16:17]
	s_cselect_b32 s7, s7, s19
	s_cselect_b32 s6, s6, s18
	s_cselect_b32 s17, s5, s21
	s_cselect_b32 s16, s4, s20
	s_add_u32 s18, s18, 0x404080
	s_addc_u32 s19, s19, 0
	s_add_u32 s57, s20, 0x100
	s_addc_u32 s58, s21, 0
	s_mov_b32 s59, -2
	s_cmp_lt_u32 s24, 0x1000
	s_cbranch_scc0 .Lf2_h1first
	ds_read_b128 v[128:131], v156
	ds_read_b128 v[132:135], v156 offset:1024
	ds_read_b128 v[150:153], v156 offset:2048
	ds_read_b128 v[162:165], v156 offset:3072
	ds_read_b128 v[166:169], v157
	ds_read_b128 v[170:173], v157 offset:1024
	ds_read_b128 v[174:177], v157 offset:2048
	ds_read_b128 v[178:181], v157 offset:3072
	s_add_u32 s20, s18, 0xffbfc080
	s_addc_u32 s21, s19, -1
	s_cmpk_eq_i32 s59, 0xfc
	s_cselect_b32 s23, s7, s21
	s_cselect_b32 s22, s6, s20
	s_cselect_b32 s21, s17, s58
	s_cselect_b32 s20, s16, s57
	ds_read_b128 v[182:185], v158
	ds_read_b128 v[186:189], v158 offset:1024
	ds_read_b128 v[190:193], v158 offset:2048
	ds_read_b128 v[194:197], v158 offset:3072
	ds_read_b128 v[198:201], v158 offset:4096
	ds_read_b128 v[202:205], v158 offset:5120
	ds_read_b128 v[206:209], v158 offset:6144
	ds_read_b128 v[210:213], v158 offset:7168
	s_add_i32 m0, s24, 0xc000
	s_nop 0
	global_load_lds_dwordx4 v136, s[18:19]
	s_add_i32 m0, s24, 0xe000
	s_nop 0
	global_load_lds_dwordx4 v140, s[18:19]
	s_waitcnt lgkmcnt(0)
	s_setprio 1
	v_mfma_f32_16x16x32_bf16 v[124:127], v[128:131], v[182:185], 0
	v_mfma_f32_16x16x32_bf16 v[120:123], v[150:153], v[182:185], 0
	v_mfma_f32_16x16x32_bf16 v[116:119], v[128:131], v[190:193], 0
	v_mfma_f32_16x16x32_bf16 v[112:115], v[150:153], v[190:193], 0
	v_mfma_f32_16x16x32_bf16 v[108:111], v[128:131], v[198:201], 0
	v_mfma_f32_16x16x32_bf16 v[104:107], v[150:153], v[198:201], 0
	v_mfma_f32_16x16x32_bf16 v[100:103], v[128:131], v[206:209], 0
	v_mfma_f32_16x16x32_bf16 v[96:99], v[150:153], v[206:209], 0
	v_mfma_f32_16x16x32_bf16 v[124:127], v[132:135], v[186:189], v[124:127]
	v_mfma_f32_16x16x32_bf16 v[120:123], v[162:165], v[186:189], v[120:123]
	v_mfma_f32_16x16x32_bf16 v[116:119], v[132:135], v[194:197], v[116:119]
	v_mfma_f32_16x16x32_bf16 v[112:115], v[162:165], v[194:197], v[112:115]
	v_mfma_f32_16x16x32_bf16 v[108:111], v[132:135], v[202:205], v[108:111]
	v_mfma_f32_16x16x32_bf16 v[104:107], v[162:165], v[202:205], v[104:107]
	v_mfma_f32_16x16x32_bf16 v[100:103], v[132:135], v[210:213], v[100:103]
	v_mfma_f32_16x16x32_bf16 v[96:99], v[162:165], v[210:213], v[96:99]
	v_mfma_f32_16x16x32_bf16 v[68:71], v[166:169], v[182:185], 0
	v_mfma_f32_16x16x32_bf16 v[64:67], v[174:177], v[182:185], 0
	v_mfma_f32_16x16x32_bf16 v[52:55], v[166:169], v[190:193], 0
	v_mfma_f32_16x16x32_bf16 v[48:51], v[174:177], v[190:193], 0
	v_mfma_f32_16x16x32_bf16 v[44:47], v[166:169], v[198:201], 0
	v_mfma_f32_16x16x32_bf16 v[40:43], v[174:177], v[198:201], 0
	v_mfma_f32_16x16x32_bf16 v[36:39], v[166:169], v[206:209], 0
	v_mfma_f32_16x16x32_bf16 v[32:35], v[174:177], v[206:209], 0
	v_mfma_f32_16x16x32_bf16 v[68:71], v[170:173], v[186:189], v[68:71]
	v_mfma_f32_16x16x32_bf16 v[64:67], v[178:181], v[186:189], v[64:67]
	v_mfma_f32_16x16x32_bf16 v[52:55], v[170:173], v[194:197], v[52:55]
	v_mfma_f32_16x16x32_bf16 v[48:51], v[178:181], v[194:197], v[48:51]
	v_mfma_f32_16x16x32_bf16 v[44:47], v[170:173], v[202:205], v[44:47]
	v_mfma_f32_16x16x32_bf16 v[40:43], v[178:181], v[202:205], v[40:43]
	v_mfma_f32_16x16x32_bf16 v[36:39], v[170:173], v[210:213], v[36:39]
	v_mfma_f32_16x16x32_bf16 v[32:35], v[178:181], v[210:213], v[32:35]
	s_setprio 0
	s_waitcnt vmcnt(8)
	s_barrier
	ds_read_b128 v[182:185], v158 offset:16384
	ds_read_b128 v[186:189], v158 offset:17408
	ds_read_b128 v[190:193], v158 offset:18432
	ds_read_b128 v[194:197], v158 offset:19456
	ds_read_b128 v[198:201], v158 offset:20480
	ds_read_b128 v[202:205], v158 offset:21504
	ds_read_b128 v[206:209], v158 offset:22528
	ds_read_b128 v[210:213], v158 offset:23552
	s_add_u32 vcc_lo, s20, 0x404000
	s_addc_u32 vcc_hi, s21, 0
	s_add_i32 m0, s24, 0x10000
	s_nop 0
	global_load_lds_dwordx4 v138, s[20:21]
	s_add_i32 m0, s24, 0x12000
	s_nop 0
	global_load_lds_dwordx4 v142, s[20:21]
	s_add_i32 m0, s24, 0x14000
	s_nop 0
	global_load_lds_dwordx4 v138, vcc
	s_add_i32 m0, s24, 0x16000
	s_nop 0
	global_load_lds_dwordx4 v142, vcc
	s_mov_b32 m0, s24
	s_nop 0
	global_load_lds_dwordx4 v136, s[22:23]
	s_add_i32 m0, s24, 0x2000
	s_nop 0
	global_load_lds_dwordx4 v140, s[22:23]
	s_waitcnt lgkmcnt(0)
	s_setprio 1
	v_mfma_f32_16x16x32_bf16 v[92:95], v[128:131], v[182:185], 0
	v_mfma_f32_16x16x32_bf16 v[88:91], v[150:153], v[182:185], 0
	v_mfma_f32_16x16x32_bf16 v[84:87], v[128:131], v[190:193], 0
	v_mfma_f32_16x16x32_bf16 v[80:83], v[150:153], v[190:193], 0
	v_mfma_f32_16x16x32_bf16 v[76:79], v[128:131], v[198:201], 0
	v_mfma_f32_16x16x32_bf16 v[72:75], v[150:153], v[198:201], 0
	v_mfma_f32_16x16x32_bf16 v[60:63], v[128:131], v[206:209], 0
	v_mfma_f32_16x16x32_bf16 v[56:59], v[150:153], v[206:209], 0
	v_mfma_f32_16x16x32_bf16 v[92:95], v[132:135], v[186:189], v[92:95]
	v_mfma_f32_16x16x32_bf16 v[88:91], v[162:165], v[186:189], v[88:91]
	v_mfma_f32_16x16x32_bf16 v[84:87], v[132:135], v[194:197], v[84:87]
	v_mfma_f32_16x16x32_bf16 v[80:83], v[162:165], v[194:197], v[80:83]
	v_mfma_f32_16x16x32_bf16 v[76:79], v[132:135], v[202:205], v[76:79]
	v_mfma_f32_16x16x32_bf16 v[72:75], v[162:165], v[202:205], v[72:75]
	v_mfma_f32_16x16x32_bf16 v[60:63], v[132:135], v[210:213], v[60:63]
	v_mfma_f32_16x16x32_bf16 v[56:59], v[162:165], v[210:213], v[56:59]
	v_mfma_f32_16x16x32_bf16 v[28:31], v[166:169], v[182:185], 0
	v_mfma_f32_16x16x32_bf16 v[24:27], v[174:177], v[182:185], 0
	v_mfma_f32_16x16x32_bf16 v[20:23], v[166:169], v[190:193], 0
	v_mfma_f32_16x16x32_bf16 v[16:19], v[174:177], v[190:193], 0
	v_mfma_f32_16x16x32_bf16 v[12:15], v[166:169], v[198:201], 0
	v_mfma_f32_16x16x32_bf16 v[8:11], v[174:177], v[198:201], 0
	v_mfma_f32_16x16x32_bf16 v[4:7], v[166:169], v[206:209], 0
	v_mfma_f32_16x16x32_bf16 v[0:3], v[174:177], v[206:209], 0
	v_mfma_f32_16x16x32_bf16 v[28:31], v[170:173], v[186:189], v[28:31]
	v_mfma_f32_16x16x32_bf16 v[24:27], v[178:181], v[186:189], v[24:27]
	v_mfma_f32_16x16x32_bf16 v[20:23], v[170:173], v[194:197], v[20:23]
	v_mfma_f32_16x16x32_bf16 v[16:19], v[178:181], v[194:197], v[16:19]
	v_mfma_f32_16x16x32_bf16 v[12:15], v[170:173], v[202:205], v[12:15]
	v_mfma_f32_16x16x32_bf16 v[8:11], v[178:181], v[202:205], v[8:11]
	v_mfma_f32_16x16x32_bf16 v[4:7], v[170:173], v[210:213], v[4:7]
	v_mfma_f32_16x16x32_bf16 v[0:3], v[178:181], v[210:213], v[0:3]
	s_setprio 0
	s_waitcnt vmcnt(8)
	s_barrier
; #define PG8_STAGE(bufoff, gbase, voff) do { _Pragma("unroll") for (int _i = 0; _i < 2; ++_i) \
;         __builtin_amdgcn_global_load_lds((const unsigned*)((const char*)(gbase) + (voff)[_i]), (PG8_LAS unsigned*)(lds + (bufoff) + ldsw + _i * 8192), 16, 0, 0); } while (0)
; #define PG8_LDA(dst, b, h) do { _Pragma("unroll") for (int m = 0; m < 4; ++m) _Pragma("unroll") for (int k = 0; k < 2; ++k) dst[m][k] = *(const PG8_LAS bf16x8*)(lds + PG8_SA(b, h) + aoff + m * 2048 + k * 1024); } while (0)
; #define PG8_LDB(dst, b, h) do { _Pragma("unroll") for (int n = 0; n < 2; ++n) _Pragma("unroll") for (int k = 0; k < 2; ++k) dst[n][k] = *(const PG8_LAS bf16x8*)(lds + PG8_SB(b, h) + boff + n * 2048 + k * 1024); } while (0)
; #define PG8_MMA(ai, bj, At, Bt) do { __builtin_amdgcn_s_setprio(1); _Pragma("unroll") for (int m = 0; m < 4; ++m) _Pragma("unroll") for (int n = 0; n < 2; ++n) _Pragma("unroll") for (int k = 0; k < 2; ++k) \
;         acc[ai][bj][m][n] = __builtin_amdgcn_mfma_f32_16x16x32_bf16(Bt[n][k], At[m][k], acc[ai][bj][m][n], 0, 0, 0); __builtin_amdgcn_s_setprio(0); } while (0)
; #define PG8_BAR __builtin_amdgcn_s_barrier()
; template <class Epi, class Sched, bool ALIGN_EPI = false, bool SP2 = false>
; __device__ __forceinline__ void gemm_phase(PG8_LAS unsigned char* lds, const Gemm g, const Sched& S, const Epi& E) {
;     ...
;             if constexpr (SP2) {
;             PG8_LDB(B0, 0, 0); PG8_LDB(B1, 0, 1); PG8_SCHED; PG8_LDA(At, 0, 0); PG8_STAGE(PG8_SA(1, 1), a1 + hstep, voffA);
;             PG8_WAIT_V(8); PG8_WAIT_L(0); PG8_BAR; PG8_MMA(0, 0, At, B0); PG8_MMA(0, 1, At, B1); PG8_BAR; PG8_SCHED;
;             PG8_LDA(At, 0, 1); PG8_STAGE(PG8_SB(0, 0), b2, voffB); PG8_STAGE(PG8_SB(0, 1), b2 + hstep, voffB); PG8_STAGE(PG8_SA(0, 0), a2, voffA);
;             PG8_WAIT_V(8); PG8_WAIT_L(0); PG8_BAR; PG8_MMA(1, 0, At, B0); PG8_MMA(1, 1, At, B1); PG8_BAR; PG8_SCHED;
;             PG8_LDB(B0, 1, 0); PG8_LDB(B1, 1, 1); PG8_SCHED; PG8_LDA(At, 1, 0); PG8_STAGE(PG8_SA(0, 1), a2 + hstep, voffA);
;             PG8_WAIT_V(8); PG8_WAIT_L(0); PG8_BAR; PG8_MMA(0, 0, At, B0); PG8_MMA(0, 1, At, B1); PG8_BAR; PG8_SCHED;
;             PG8_LDA(At, 1, 1); PG8_STAGE(PG8_SB(1, 0), b3, voffB); PG8_STAGE(PG8_SB(1, 1), b3 + hstep, voffB); PG8_STAGE(PG8_SA(1, 0), a3, voffA);
;             PG8_WAIT_V(8); PG8_WAIT_L(0); PG8_BAR; PG8_MMA(1, 0, At, B0); PG8_MMA(1, 1, At, B1); PG8_BAR; PG8_SCHED;
	ds_read_b128 v[128:131], v159
	ds_read_b128 v[132:135], v159 offset:1024
	ds_read_b128 v[150:153], v159 offset:2048
	ds_read_b128 v[162:165], v159 offset:3072
	ds_read_b128 v[166:169], v160
	ds_read_b128 v[170:173], v160 offset:1024
	ds_read_b128 v[174:177], v160 offset:2048
	ds_read_b128 v[178:181], v160 offset:3072
	ds_read_b128 v[182:185], v158 offset:32768
	ds_read_b128 v[186:189], v158 offset:33792
	ds_read_b128 v[190:193], v158 offset:34816
	ds_read_b128 v[194:197], v158 offset:35840
	ds_read_b128 v[198:201], v158 offset:36864
	ds_read_b128 v[202:205], v158 offset:37888
	ds_read_b128 v[206:209], v158 offset:38912
	ds_read_b128 v[210:213], v158 offset:39936
	s_add_u32 vcc_lo, s22, 0x404000
	s_addc_u32 vcc_hi, s23, 0
	s_add_i32 m0, s24, 0x4000
	s_nop 0
	global_load_lds_dwordx4 v136, vcc
	s_add_i32 m0, s24, 0x6000
	s_nop 0
	global_load_lds_dwordx4 v140, vcc
	s_waitcnt lgkmcnt(0)
	s_setprio 1
	v_mfma_f32_16x16x32_bf16 v[124:127], v[128:131], v[182:185], v[124:127]
	v_mfma_f32_16x16x32_bf16 v[120:123], v[150:153], v[182:185], v[120:123]
	v_mfma_f32_16x16x32_bf16 v[116:119], v[128:131], v[190:193], v[116:119]
	v_mfma_f32_16x16x32_bf16 v[112:115], v[150:153], v[190:193], v[112:115]
	v_mfma_f32_16x16x32_bf16 v[108:111], v[128:131], v[198:201], v[108:111]
	v_mfma_f32_16x16x32_bf16 v[104:107], v[150:153], v[198:201], v[104:107]
	v_mfma_f32_16x16x32_bf16 v[100:103], v[128:131], v[206:209], v[100:103]
	v_mfma_f32_16x16x32_bf16 v[96:99], v[150:153], v[206:209], v[96:99]
	v_mfma_f32_16x16x32_bf16 v[124:127], v[132:135], v[186:189], v[124:127]
	v_mfma_f32_16x16x32_bf16 v[120:123], v[162:165], v[186:189], v[120:123]
	v_mfma_f32_16x16x32_bf16 v[116:119], v[132:135], v[194:197], v[116:119]
	v_mfma_f32_16x16x32_bf16 v[112:115], v[162:165], v[194:197], v[112:115]
	v_mfma_f32_16x16x32_bf16 v[108:111], v[132:135], v[202:205], v[108:111]
	v_mfma_f32_16x16x32_bf16 v[104:107], v[162:165], v[202:205], v[104:107]
	v_mfma_f32_16x16x32_bf16 v[100:103], v[132:135], v[210:213], v[100:103]
	v_mfma_f32_16x16x32_bf16 v[96:99], v[162:165], v[210:213], v[96:99]
	v_mfma_f32_16x16x32_bf16 v[68:71], v[166:169], v[182:185], v[68:71]
	v_mfma_f32_16x16x32_bf16 v[64:67], v[174:177], v[182:185], v[64:67]
	v_mfma_f32_16x16x32_bf16 v[52:55], v[166:169], v[190:193], v[52:55]
	v_mfma_f32_16x16x32_bf16 v[48:51], v[174:177], v[190:193], v[48:51]
	v_mfma_f32_16x16x32_bf16 v[44:47], v[166:169], v[198:201], v[44:47]
	v_mfma_f32_16x16x32_bf16 v[40:43], v[174:177], v[198:201], v[40:43]
	v_mfma_f32_16x16x32_bf16 v[36:39], v[166:169], v[206:209], v[36:39]
	v_mfma_f32_16x16x32_bf16 v[32:35], v[174:177], v[206:209], v[32:35]
	v_mfma_f32_16x16x32_bf16 v[68:71], v[170:173], v[186:189], v[68:71]
	v_mfma_f32_16x16x32_bf16 v[64:67], v[178:181], v[186:189], v[64:67]
	v_mfma_f32_16x16x32_bf16 v[52:55], v[170:173], v[194:197], v[52:55]
	v_mfma_f32_16x16x32_bf16 v[48:51], v[178:181], v[194:197], v[48:51]
	v_mfma_f32_16x16x32_bf16 v[44:47], v[170:173], v[202:205], v[44:47]
	v_mfma_f32_16x16x32_bf16 v[40:43], v[178:181], v[202:205], v[40:43]
	v_mfma_f32_16x16x32_bf16 v[36:39], v[170:173], v[210:213], v[36:39]
	v_mfma_f32_16x16x32_bf16 v[32:35], v[178:181], v[210:213], v[32:35]
	s_setprio 0
	s_waitcnt vmcnt(8)
	s_barrier
	ds_read_b128 v[182:185], v158 offset:49152
	ds_read_b128 v[186:189], v158 offset:50176
	ds_read_b128 v[190:193], v158 offset:51200
	ds_read_b128 v[194:197], v158 offset:52224
	ds_read_b128 v[198:201], v158 offset:53248
	ds_read_b128 v[202:205], v158 offset:54272
	ds_read_b128 v[206:209], v158 offset:55296
	ds_read_b128 v[210:213], v158 offset:56320
	s_add_u32 s60, s20, 0x80
	s_addc_u32 s61, s21, 0
	s_add_u32 vcc_lo, s60, 0x404000
	s_addc_u32 vcc_hi, s61, 0
	s_add_i32 m0, s24, 0x18000
	s_nop 0
	global_load_lds_dwordx4 v138, s[60:61]
	s_add_i32 m0, s24, 0x1a000
	s_nop 0
	global_load_lds_dwordx4 v142, s[60:61]
	s_add_i32 m0, s24, 0x1c000
	s_nop 0
	global_load_lds_dwordx4 v138, vcc
	s_add_i32 m0, s24, 0x1e000
	s_nop 0
	global_load_lds_dwordx4 v142, vcc
	s_add_u32 s60, s22, 0x80
	s_addc_u32 s61, s23, 0
	s_add_i32 m0, s24, 0x8000
	s_nop 0
	global_load_lds_dwordx4 v136, s[60:61]
	s_add_i32 m0, s24, 0xa000
	s_nop 0
	global_load_lds_dwordx4 v140, s[60:61]
	s_waitcnt lgkmcnt(0)
	s_setprio 1
	v_mfma_f32_16x16x32_bf16 v[92:95], v[128:131], v[182:185], v[92:95]
	v_mfma_f32_16x16x32_bf16 v[88:91], v[150:153], v[182:185], v[88:91]
	v_mfma_f32_16x16x32_bf16 v[84:87], v[128:131], v[190:193], v[84:87]
	v_mfma_f32_16x16x32_bf16 v[80:83], v[150:153], v[190:193], v[80:83]
	v_mfma_f32_16x16x32_bf16 v[76:79], v[128:131], v[198:201], v[76:79]
	v_mfma_f32_16x16x32_bf16 v[72:75], v[150:153], v[198:201], v[72:75]
	v_mfma_f32_16x16x32_bf16 v[60:63], v[128:131], v[206:209], v[60:63]
	v_mfma_f32_16x16x32_bf16 v[56:59], v[150:153], v[206:209], v[56:59]
	v_mfma_f32_16x16x32_bf16 v[92:95], v[132:135], v[186:189], v[92:95]
	v_mfma_f32_16x16x32_bf16 v[88:91], v[162:165], v[186:189], v[88:91]
	v_mfma_f32_16x16x32_bf16 v[84:87], v[132:135], v[194:197], v[84:87]
	v_mfma_f32_16x16x32_bf16 v[80:83], v[162:165], v[194:197], v[80:83]
	v_mfma_f32_16x16x32_bf16 v[76:79], v[132:135], v[202:205], v[76:79]
	v_mfma_f32_16x16x32_bf16 v[72:75], v[162:165], v[202:205], v[72:75]
	v_mfma_f32_16x16x32_bf16 v[60:63], v[132:135], v[210:213], v[60:63]
	v_mfma_f32_16x16x32_bf16 v[56:59], v[162:165], v[210:213], v[56:59]
	v_mfma_f32_16x16x32_bf16 v[28:31], v[166:169], v[182:185], v[28:31]
	v_mfma_f32_16x16x32_bf16 v[24:27], v[174:177], v[182:185], v[24:27]
	v_mfma_f32_16x16x32_bf16 v[20:23], v[166:169], v[190:193], v[20:23]
	v_mfma_f32_16x16x32_bf16 v[16:19], v[174:177], v[190:193], v[16:19]
	v_mfma_f32_16x16x32_bf16 v[12:15], v[166:169], v[198:201], v[12:15]
	v_mfma_f32_16x16x32_bf16 v[8:11], v[174:177], v[198:201], v[8:11]
	v_mfma_f32_16x16x32_bf16 v[4:7], v[166:169], v[206:209], v[4:7]
	v_mfma_f32_16x16x32_bf16 v[0:3], v[174:177], v[206:209], v[0:3]
	v_mfma_f32_16x16x32_bf16 v[28:31], v[170:173], v[186:189], v[28:31]
	v_mfma_f32_16x16x32_bf16 v[24:27], v[178:181], v[186:189], v[24:27]
	v_mfma_f32_16x16x32_bf16 v[20:23], v[170:173], v[194:197], v[20:23]
	v_mfma_f32_16x16x32_bf16 v[16:19], v[178:181], v[194:197], v[16:19]
	v_mfma_f32_16x16x32_bf16 v[12:15], v[170:173], v[202:205], v[12:15]
	v_mfma_f32_16x16x32_bf16 v[8:11], v[178:181], v[202:205], v[8:11]
	v_mfma_f32_16x16x32_bf16 v[4:7], v[170:173], v[210:213], v[4:7]
	v_mfma_f32_16x16x32_bf16 v[0:3], v[178:181], v[210:213], v[0:3]
	s_setprio 0
	s_waitcnt vmcnt(8)
	s_barrier
	s_add_i32 s59, s59, 2
	s_add_u32 s18, s18, 0x100
	s_addc_u32 s19, s19, 0
	s_add_u32 s57, s57, 0x100
	s_addc_u32 s58, s58, 0
	s_cmpk_gt_u32 s59, 0xfd

; #define PG8_STAGE(bufoff, gbase, voff) do { _Pragma("unroll") for (int _i = 0; _i < 2; ++_i) \
;         __builtin_amdgcn_global_load_lds((const unsigned*)((const char*)(gbase) + (voff)[_i]), (PG8_LAS unsigned*)(lds + (bufoff) + ldsw + _i * 8192), 16, 0, 0); } while (0)
; #define PG8_LDA(dst, b, h) do { _Pragma("unroll") for (int m = 0; m < 4; ++m) _Pragma("unroll") for (int k = 0; k < 2; ++k) dst[m][k] = *(const PG8_LAS bf16x8*)(lds + PG8_SA(b, h) + aoff + m * 2048 + k * 1024); } while (0)
; #define PG8_LDB(dst, b, h) do { _Pragma("unroll") for (int n = 0; n < 2; ++n) _Pragma("unroll") for (int k = 0; k < 2; ++k) dst[n][k] = *(const PG8_LAS bf16x8*)(lds + PG8_SB(b, h) + boff + n * 2048 + k * 1024); } while (0)
; #define PG8_MMA(ai, bj, At, Bt) do { __builtin_amdgcn_s_setprio(1); _Pragma("unroll") for (int m = 0; m < 4; ++m) _Pragma("unroll") for (int n = 0; n < 2; ++n) _Pragma("unroll") for (int k = 0; k < 2; ++k) \
;         acc[ai][bj][m][n] = __builtin_amdgcn_mfma_f32_16x16x32_bf16(Bt[n][k], At[m][k], acc[ai][bj][m][n], 0, 0, 0); __builtin_amdgcn_s_setprio(0); } while (0)
; #define PG8_BAR __builtin_amdgcn_s_barrier()
; template <class Epi, class Sched, bool ALIGN_EPI = false, bool SP2 = false>
; __device__ __forceinline__ void gemm_phase(PG8_LAS unsigned char* lds, const Gemm g, const Sched& S, const Epi& E) {
;     ...
;             if constexpr (SP2) {
;             PG8_LDB(B0, 0, 0); PG8_LDB(B1, 0, 1); PG8_SCHED; PG8_LDA(At, 0, 0); PG8_STAGE(PG8_SA(1, 1), a1 + hstep, voffA);
;             PG8_WAIT_V(8); PG8_WAIT_L(0); PG8_BAR; PG8_MMA(0, 0, At, B0); PG8_MMA(0, 1, At, B1); PG8_BAR; PG8_SCHED;
;             PG8_LDA(At, 0, 1); PG8_STAGE(PG8_SB(0, 0), b2, voffB); PG8_STAGE(PG8_SB(0, 1), b2 + hstep, voffB); PG8_STAGE(PG8_SA(0, 0), a2, voffA);
;             PG8_WAIT_V(8); PG8_WAIT_L(0); PG8_BAR; PG8_MMA(1, 0, At, B0); PG8_MMA(1, 1, At, B1); PG8_BAR; PG8_SCHED;
;             PG8_LDB(B0, 1, 0); PG8_LDB(B1, 1, 1); PG8_SCHED; PG8_LDA(At, 1, 0); PG8_STAGE(PG8_SA(0, 1), a2 + hstep, voffA);
;             PG8_WAIT_V(8); PG8_WAIT_L(0); PG8_BAR; PG8_MMA(0, 0, At, B0); PG8_MMA(0, 1, At, B1); PG8_BAR; PG8_SCHED;
;             PG8_LDA(At, 1, 1); PG8_STAGE(PG8_SB(1, 0), b3, voffB); PG8_STAGE(PG8_SB(1, 1), b3 + hstep, voffB); PG8_STAGE(PG8_SA(1, 0), a3, voffA);
;             PG8_WAIT_V(8); PG8_WAIT_L(0); PG8_BAR; PG8_MMA(1, 0, At, B0); PG8_MMA(1, 1, At, B1); PG8_BAR; PG8_SCHED;
.Lf2_h1first:
	ds_read_b128 v[128:131], v156
	ds_read_b128 v[132:135], v156 offset:1024
	ds_read_b128 v[150:153], v156 offset:2048
	ds_read_b128 v[162:165], v156 offset:3072
	ds_read_b128 v[166:169], v157
	ds_read_b128 v[170:173], v157 offset:1024
	ds_read_b128 v[174:177], v157 offset:2048
	ds_read_b128 v[178:181], v157 offset:3072
	s_add_u32 s20, s18, 0xffbfc080
	s_addc_u32 s21, s19, -1
	s_cmpk_eq_i32 s59, 0xfc
	s_cselect_b32 s23, s7, s21
	s_cselect_b32 s22, s6, s20
	s_cselect_b32 s21, s17, s58
	s_cselect_b32 s20, s16, s57
	ds_read_b128 v[182:185], v158
	ds_read_b128 v[186:189], v158 offset:1024
	ds_read_b128 v[190:193], v158 offset:2048
	ds_read_b128 v[194:197], v158 offset:3072
	ds_read_b128 v[198:201], v158 offset:4096
	ds_read_b128 v[202:205], v158 offset:5120
	ds_read_b128 v[206:209], v158 offset:6144
	ds_read_b128 v[210:213], v158 offset:7168
	s_add_i32 m0, s24, 0xc000
	s_nop 0
	global_load_lds_dwordx4 v136, s[18:19]
	s_add_i32 m0, s24, 0xe000
	s_nop 0
	global_load_lds_dwordx4 v140, s[18:19]
	s_sleep 2
	s_waitcnt lgkmcnt(0)
	s_waitcnt vmcnt(8)
	s_barrier
	s_setprio 2
	v_mfma_f32_16x16x32_bf16 v[124:127], v[128:131], v[182:185], 0
	v_mfma_f32_16x16x32_bf16 v[120:123], v[150:153], v[182:185], 0
	v_mfma_f32_16x16x32_bf16 v[116:119], v[128:131], v[190:193], 0
	v_mfma_f32_16x16x32_bf16 v[112:115], v[150:153], v[190:193], 0
	v_mfma_f32_16x16x32_bf16 v[108:111], v[128:131], v[198:201], 0
	v_mfma_f32_16x16x32_bf16 v[104:107], v[150:153], v[198:201], 0
	v_mfma_f32_16x16x32_bf16 v[100:103], v[128:131], v[206:209], 0
	v_mfma_f32_16x16x32_bf16 v[96:99], v[150:153], v[206:209], 0
	v_mfma_f32_16x16x32_bf16 v[124:127], v[132:135], v[186:189], v[124:127]
	v_mfma_f32_16x16x32_bf16 v[120:123], v[162:165], v[186:189], v[120:123]
	v_mfma_f32_16x16x32_bf16 v[116:119], v[132:135], v[194:197], v[116:119]
	v_mfma_f32_16x16x32_bf16 v[112:115], v[162:165], v[194:197], v[112:115]
	v_mfma_f32_16x16x32_bf16 v[108:111], v[132:135], v[202:205], v[108:111]
	v_mfma_f32_16x16x32_bf16 v[104:107], v[162:165], v[202:205], v[104:107]
	v_mfma_f32_16x16x32_bf16 v[100:103], v[132:135], v[210:213], v[100:103]
	v_mfma_f32_16x16x32_bf16 v[96:99], v[162:165], v[210:213], v[96:99]
	v_mfma_f32_16x16x32_bf16 v[68:71], v[166:169], v[182:185], 0
	v_mfma_f32_16x16x32_bf16 v[64:67], v[174:177], v[182:185], 0
	v_mfma_f32_16x16x32_bf16 v[52:55], v[166:169], v[190:193], 0
	v_mfma_f32_16x16x32_bf16 v[48:51], v[174:177], v[190:193], 0
	v_mfma_f32_16x16x32_bf16 v[44:47], v[166:169], v[198:201], 0
	v_mfma_f32_16x16x32_bf16 v[40:43], v[174:177], v[198:201], 0
	v_mfma_f32_16x16x32_bf16 v[36:39], v[166:169], v[206:209], 0
	v_mfma_f32_16x16x32_bf16 v[32:35], v[174:177], v[206:209], 0
	v_mfma_f32_16x16x32_bf16 v[68:71], v[170:173], v[186:189], v[68:71]
	v_mfma_f32_16x16x32_bf16 v[64:67], v[178:181], v[186:189], v[64:67]
	v_mfma_f32_16x16x32_bf16 v[52:55], v[170:173], v[194:197], v[52:55]
	v_mfma_f32_16x16x32_bf16 v[48:51], v[178:181], v[194:197], v[48:51]
	v_mfma_f32_16x16x32_bf16 v[44:47], v[170:173], v[202:205], v[44:47]
	v_mfma_f32_16x16x32_bf16 v[40:43], v[178:181], v[202:205], v[40:43]
	v_mfma_f32_16x16x32_bf16 v[36:39], v[170:173], v[210:213], v[36:39]
	v_mfma_f32_16x16x32_bf16 v[32:35], v[178:181], v[210:213], v[32:35]
	s_setprio 0
	ds_read_b128 v[182:185], v158 offset:16384
	ds_read_b128 v[186:189], v158 offset:17408
	ds_read_b128 v[190:193], v158 offset:18432
	ds_read_b128 v[194:197], v158 offset:19456
	ds_read_b128 v[198:201], v158 offset:20480
	ds_read_b128 v[202:205], v158 offset:21504
	ds_read_b128 v[206:209], v158 offset:22528
	ds_read_b128 v[210:213], v158 offset:23552
	s_add_u32 vcc_lo, s20, 0x404000
	s_addc_u32 vcc_hi, s21, 0
	s_add_i32 m0, s24, 0x10000
	s_nop 0
	global_load_lds_dwordx4 v138, s[20:21]
	s_add_i32 m0, s24, 0x12000
	s_nop 0
	global_load_lds_dwordx4 v142, s[20:21]
	s_add_i32 m0, s24, 0x14000
	s_nop 0
	global_load_lds_dwordx4 v138, vcc
	s_add_i32 m0, s24, 0x16000
	s_nop 0
	global_load_lds_dwordx4 v142, vcc
	s_mov_b32 m0, s24
	s_nop 0
	global_load_lds_dwordx4 v136, s[22:23]
	s_add_i32 m0, s24, 0x2000
	s_nop 0
	global_load_lds_dwordx4 v140, s[22:23]
	s_sleep 2
	s_waitcnt lgkmcnt(0)
	s_waitcnt vmcnt(8)
	s_barrier
	s_setprio 2
	v_mfma_f32_16x16x32_bf16 v[92:95], v[128:131], v[182:185], 0
	v_mfma_f32_16x16x32_bf16 v[88:91], v[150:153], v[182:185], 0
	v_mfma_f32_16x16x32_bf16 v[84:87], v[128:131], v[190:193], 0
	v_mfma_f32_16x16x32_bf16 v[80:83], v[150:153], v[190:193], 0
	v_mfma_f32_16x16x32_bf16 v[76:79], v[128:131], v[198:201], 0
	v_mfma_f32_16x16x32_bf16 v[72:75], v[150:153], v[198:201], 0
	v_mfma_f32_16x16x32_bf16 v[60:63], v[128:131], v[206:209], 0
	v_mfma_f32_16x16x32_bf16 v[56:59], v[150:153], v[206:209], 0
	v_mfma_f32_16x16x32_bf16 v[92:95], v[132:135], v[186:189], v[92:95]
	v_mfma_f32_16x16x32_bf16 v[88:91], v[162:165], v[186:189], v[88:91]
	v_mfma_f32_16x16x32_bf16 v[84:87], v[132:135], v[194:197], v[84:87]
	v_mfma_f32_16x16x32_bf16 v[80:83], v[162:165], v[194:197], v[80:83]
	v_mfma_f32_16x16x32_bf16 v[76:79], v[132:135], v[202:205], v[76:79]
	v_mfma_f32_16x16x32_bf16 v[72:75], v[162:165], v[202:205], v[72:75]
	v_mfma_f32_16x16x32_bf16 v[60:63], v[132:135], v[210:213], v[60:63]
	v_mfma_f32_16x16x32_bf16 v[56:59], v[162:165], v[210:213], v[56:59]
	v_mfma_f32_16x16x32_bf16 v[28:31], v[166:169], v[182:185], 0
	v_mfma_f32_16x16x32_bf16 v[24:27], v[174:177], v[182:185], 0
	v_mfma_f32_16x16x32_bf16 v[20:23], v[166:169], v[190:193], 0
	v_mfma_f32_16x16x32_bf16 v[16:19], v[174:177], v[190:193], 0
	v_mfma_f32_16x16x32_bf16 v[12:15], v[166:169], v[198:201], 0
	v_mfma_f32_16x16x32_bf16 v[8:11], v[174:177], v[198:201], 0
	v_mfma_f32_16x16x32_bf16 v[4:7], v[166:169], v[206:209], 0
; #define PG8_STAGE(bufoff, gbase, voff) do { _Pragma("unroll") for (int _i = 0; _i < 2; ++_i) \
;         __builtin_amdgcn_global_load_lds((const unsigned*)((const char*)(gbase) + (voff)[_i]), (PG8_LAS unsigned*)(lds + (bufoff) + ldsw + _i * 8192), 16, 0, 0); } while (0)
; #define PG8_LDA(dst, b, h) do { _Pragma("unroll") for (int m = 0; m < 4; ++m) _Pragma("unroll") for (int k = 0; k < 2; ++k) dst[m][k] = *(const PG8_LAS bf16x8*)(lds + PG8_SA(b, h) + aoff + m * 2048 + k * 1024); } while (0)
; #define PG8_LDB(dst, b, h) do { _Pragma("unroll") for (int n = 0; n < 2; ++n) _Pragma("unroll") for (int k = 0; k < 2; ++k) dst[n][k] = *(const PG8_LAS bf16x8*)(lds + PG8_SB(b, h) + boff + n * 2048 + k * 1024); } while (0)
; #define PG8_MMA(ai, bj, At, Bt) do { __builtin_amdgcn_s_setprio(1); _Pragma("unroll") for (int m = 0; m < 4; ++m) _Pragma("unroll") for (int n = 0; n < 2; ++n) _Pragma("unroll") for (int k = 0; k < 2; ++k) \
;         acc[ai][bj][m][n] = __builtin_amdgcn_mfma_f32_16x16x32_bf16(Bt[n][k], At[m][k], acc[ai][bj][m][n], 0, 0, 0); __builtin_amdgcn_s_setprio(0); } while (0)
; #define PG8_BAR __builtin_amdgcn_s_barrier()
; template <class Epi, class Sched, bool ALIGN_EPI = false, bool SP2 = false>
; __device__ __forceinline__ void gemm_phase(PG8_LAS unsigned char* lds, const Gemm g, const Sched& S, const Epi& E) {
;     ...
;             if constexpr (SP2) {
;             PG8_LDB(B0, 0, 0); PG8_LDB(B1, 0, 1); PG8_SCHED; PG8_LDA(At, 0, 0); PG8_STAGE(PG8_SA(1, 1), a1 + hstep, voffA);
;             PG8_WAIT_V(8); PG8_WAIT_L(0); PG8_BAR; PG8_MMA(0, 0, At, B0); PG8_MMA(0, 1, At, B1); PG8_BAR; PG8_SCHED;
;             PG8_LDA(At, 0, 1); PG8_STAGE(PG8_SB(0, 0), b2, voffB); PG8_STAGE(PG8_SB(0, 1), b2 + hstep, voffB); PG8_STAGE(PG8_SA(0, 0), a2, voffA);
;             PG8_WAIT_V(8); PG8_WAIT_L(0); PG8_BAR; PG8_MMA(1, 0, At, B0); PG8_MMA(1, 1, At, B1); PG8_BAR; PG8_SCHED;
;             PG8_LDB(B0, 1, 0); PG8_LDB(B1, 1, 1); PG8_SCHED; PG8_LDA(At, 1, 0); PG8_STAGE(PG8_SA(0, 1), a2 + hstep, voffA);
;             PG8_WAIT_V(8); PG8_WAIT_L(0); PG8_BAR; PG8_MMA(0, 0, At, B0); PG8_MMA(0, 1, At, B1); PG8_BAR; PG8_SCHED;
;             PG8_LDA(At, 1, 1); PG8_STAGE(PG8_SB(1, 0), b3, voffB); PG8_STAGE(PG8_SB(1, 1), b3 + hstep, voffB); PG8_STAGE(PG8_SA(1, 0), a3, voffA);
;             PG8_WAIT_V(8); PG8_WAIT_L(0); PG8_BAR; PG8_MMA(1, 0, At, B0); PG8_MMA(1, 1, At, B1); PG8_BAR; PG8_SCHED;
	v_mfma_f32_16x16x32_bf16 v[0:3], v[174:177], v[206:209], 0
	v_mfma_f32_16x16x32_bf16 v[28:31], v[170:173], v[186:189], v[28:31]
	v_mfma_f32_16x16x32_bf16 v[24:27], v[178:181], v[186:189], v[24:27]
	v_mfma_f32_16x16x32_bf16 v[20:23], v[170:173], v[194:197], v[20:23]
	v_mfma_f32_16x16x32_bf16 v[16:19], v[178:181], v[194:197], v[16:19]
	v_mfma_f32_16x16x32_bf16 v[12:15], v[170:173], v[202:205], v[12:15]
	v_mfma_f32_16x16x32_bf16 v[8:11], v[178:181], v[202:205], v[8:11]
	v_mfma_f32_16x16x32_bf16 v[4:7], v[170:173], v[210:213], v[4:7]
	v_mfma_f32_16x16x32_bf16 v[0:3], v[178:181], v[210:213], v[0:3]
	s_setprio 0
	ds_read_b128 v[128:131], v159
	ds_read_b128 v[132:135], v159 offset:1024
	ds_read_b128 v[150:153], v159 offset:2048
	ds_read_b128 v[162:165], v159 offset:3072
	ds_read_b128 v[166:169], v160
	ds_read_b128 v[170:173], v160 offset:1024
	ds_read_b128 v[174:177], v160 offset:2048
	ds_read_b128 v[178:181], v160 offset:3072
	ds_read_b128 v[182:185], v158 offset:32768
	ds_read_b128 v[186:189], v158 offset:33792
	ds_read_b128 v[190:193], v158 offset:34816
	ds_read_b128 v[194:197], v158 offset:35840
	ds_read_b128 v[198:201], v158 offset:36864
	ds_read_b128 v[202:205], v158 offset:37888
	ds_read_b128 v[206:209], v158 offset:38912
	ds_read_b128 v[210:213], v158 offset:39936
	s_add_u32 vcc_lo, s22, 0x404000
	s_addc_u32 vcc_hi, s23, 0
	s_add_i32 m0, s24, 0x4000
	s_nop 0
	global_load_lds_dwordx4 v136, vcc
	s_add_i32 m0, s24, 0x6000
	s_nop 0
	global_load_lds_dwordx4 v140, vcc
	s_sleep 2
	s_waitcnt lgkmcnt(0)
	s_waitcnt vmcnt(8)
	s_barrier
	s_setprio 2
	v_mfma_f32_16x16x32_bf16 v[124:127], v[128:131], v[182:185], v[124:127]
	v_mfma_f32_16x16x32_bf16 v[120:123], v[150:153], v[182:185], v[120:123]
	v_mfma_f32_16x16x32_bf16 v[116:119], v[128:131], v[190:193], v[116:119]
	v_mfma_f32_16x16x32_bf16 v[112:115], v[150:153], v[190:193], v[112:115]
	v_mfma_f32_16x16x32_bf16 v[108:111], v[128:131], v[198:201], v[108:111]
	v_mfma_f32_16x16x32_bf16 v[104:107], v[150:153], v[198:201], v[104:107]
	v_mfma_f32_16x16x32_bf16 v[100:103], v[128:131], v[206:209], v[100:103]
	v_mfma_f32_16x16x32_bf16 v[96:99], v[150:153], v[206:209], v[96:99]
	v_mfma_f32_16x16x32_bf16 v[124:127], v[132:135], v[186:189], v[124:127]
	v_mfma_f32_16x16x32_bf16 v[120:123], v[162:165], v[186:189], v[120:123]
	v_mfma_f32_16x16x32_bf16 v[116:119], v[132:135], v[194:197], v[116:119]
	v_mfma_f32_16x16x32_bf16 v[112:115], v[162:165], v[194:197], v[112:115]
	v_mfma_f32_16x16x32_bf16 v[108:111], v[132:135], v[202:205], v[108:111]
	v_mfma_f32_16x16x32_bf16 v[104:107], v[162:165], v[202:205], v[104:107]
	v_mfma_f32_16x16x32_bf16 v[100:103], v[132:135], v[210:213], v[100:103]
	v_mfma_f32_16x16x32_bf16 v[96:99], v[162:165], v[210:213], v[96:99]
	v_mfma_f32_16x16x32_bf16 v[68:71], v[166:169], v[182:185], v[68:71]
	v_mfma_f32_16x16x32_bf16 v[64:67], v[174:177], v[182:185], v[64:67]
	v_mfma_f32_16x16x32_bf16 v[52:55], v[166:169], v[190:193], v[52:55]
	v_mfma_f32_16x16x32_bf16 v[48:51], v[174:177], v[190:193], v[48:51]
	v_mfma_f32_16x16x32_bf16 v[44:47], v[166:169], v[198:201], v[44:47]
	v_mfma_f32_16x16x32_bf16 v[40:43], v[174:177], v[198:201], v[40:43]
	v_mfma_f32_16x16x32_bf16 v[36:39], v[166:169], v[206:209], v[36:39]
	v_mfma_f32_16x16x32_bf16 v[32:35], v[174:177], v[206:209], v[32:35]
	v_mfma_f32_16x16x32_bf16 v[68:71], v[170:173], v[186:189], v[68:71]
	v_mfma_f32_16x16x32_bf16 v[64:67], v[178:181], v[186:189], v[64:67]
	v_mfma_f32_16x16x32_bf16 v[52:55], v[170:173], v[194:197], v[52:55]
	v_mfma_f32_16x16x32_bf16 v[48:51], v[178:181], v[194:197], v[48:51]
	v_mfma_f32_16x16x32_bf16 v[44:47], v[170:173], v[202:205], v[44:47]
	v_mfma_f32_16x16x32_bf16 v[40:43], v[178:181], v[202:205], v[40:43]
	v_mfma_f32_16x16x32_bf16 v[36:39], v[170:173], v[210:213], v[36:39]
	v_mfma_f32_16x16x32_bf16 v[32:35], v[178:181], v[210:213], v[32:35]
	s_setprio 0
	ds_read_b128 v[182:185], v158 offset:49152
	ds_read_b128 v[186:189], v158 offset:50176
	ds_read_b128 v[190:193], v158 offset:51200
	ds_read_b128 v[194:197], v158 offset:52224
	ds_read_b128 v[198:201], v158 offset:53248
	ds_read_b128 v[202:205], v158 offset:54272
	ds_read_b128 v[206:209], v158 offset:55296
	ds_read_b128 v[210:213], v158 offset:56320
	s_add_u32 s60, s20, 0x80
	s_addc_u32 s61, s21, 0
	s_add_u32 vcc_lo, s60, 0x404000
	s_addc_u32 vcc_hi, s61, 0
	s_add_i32 m0, s24, 0x18000
	s_nop 0
	global_load_lds_dwordx4 v138, s[60:61]
	s_add_i32 m0, s24, 0x1a000
	s_nop 0
	global_load_lds_dwordx4 v142, s[60:61]
	s_add_i32 m0, s24, 0x1c000
	s_nop 0
	global_load_lds_dwordx4 v138, vcc
	s_add_i32 m0, s24, 0x1e000
	s_nop 0
	global_load_lds_dwordx4 v142, vcc
	s_add_u32 s60, s22, 0x80
	s_addc_u32 s61, s23, 0
	s_add_i32 m0, s24, 0x8000
	s_nop 0
	global_load_lds_dwordx4 v136, s[60:61]
	s_add_i32 m0, s24, 0xa000
	s_nop 0
	global_load_lds_dwordx4 v140, s[60:61]
	s_sleep 2
	s_waitcnt lgkmcnt(0)
	s_waitcnt vmcnt(8)
	s_barrier
; #define PG8_STAGE(bufoff, gbase, voff) do { _Pragma("unroll") for (int _i = 0; _i < 2; ++_i) \
;         __builtin_amdgcn_global_load_lds((const unsigned*)((const char*)(gbase) + (voff)[_i]), (PG8_LAS unsigned*)(lds + (bufoff) + ldsw + _i * 8192), 16, 0, 0); } while (0)
; #define PG8_LDA(dst, b, h) do { _Pragma("unroll") for (int m = 0; m < 4; ++m) _Pragma("unroll") for (int k = 0; k < 2; ++k) dst[m][k] = *(const PG8_LAS bf16x8*)(lds + PG8_SA(b, h) + aoff + m * 2048 + k * 1024); } while (0)
; #define PG8_LDB(dst, b, h) do { _Pragma("unroll") for (int n = 0; n < 2; ++n) _Pragma("unroll") for (int k = 0; k < 2; ++k) dst[n][k] = *(const PG8_LAS bf16x8*)(lds + PG8_SB(b, h) + boff + n * 2048 + k * 1024); } while (0)
; #define PG8_MMA(ai, bj, At, Bt) do { __builtin_amdgcn_s_setprio(1); _Pragma("unroll") for (int m = 0; m < 4; ++m) _Pragma("unroll") for (int n = 0; n < 2; ++n) _Pragma("unroll") for (int k = 0; k < 2; ++k) \
;         acc[ai][bj][m][n] = __builtin_amdgcn_mfma_f32_16x16x32_bf16(Bt[n][k], At[m][k], acc[ai][bj][m][n], 0, 0, 0); __builtin_amdgcn_s_setprio(0); } while (0)
; #define PG8_BAR __builtin_amdgcn_s_barrier()
; template <class Epi, class Sched, bool ALIGN_EPI = false, bool SP2 = false>
; __device__ __forceinline__ void gemm_phase(PG8_LAS unsigned char* lds, const Gemm g, const Sched& S, const Epi& E) {
;     ...
;             if constexpr (SP2) {
;             PG8_LDB(B0, 0, 0); PG8_LDB(B1, 0, 1); PG8_SCHED; PG8_LDA(At, 0, 0); PG8_STAGE(PG8_SA(1, 1), a1 + hstep, voffA);
;             PG8_WAIT_V(8); PG8_WAIT_L(0); PG8_BAR; PG8_MMA(0, 0, At, B0); PG8_MMA(0, 1, At, B1); PG8_BAR; PG8_SCHED;
;             PG8_LDA(At, 0, 1); PG8_STAGE(PG8_SB(0, 0), b2, voffB); PG8_STAGE(PG8_SB(0, 1), b2 + hstep, voffB); PG8_STAGE(PG8_SA(0, 0), a2, voffA);
;             PG8_WAIT_V(8); PG8_WAIT_L(0); PG8_BAR; PG8_MMA(1, 0, At, B0); PG8_MMA(1, 1, At, B1); PG8_BAR; PG8_SCHED;
;             PG8_LDB(B0, 1, 0); PG8_LDB(B1, 1, 1); PG8_SCHED; PG8_LDA(At, 1, 0); PG8_STAGE(PG8_SA(0, 1), a2 + hstep, voffA);
;             PG8_WAIT_V(8); PG8_WAIT_L(0); PG8_BAR; PG8_MMA(0, 0, At, B0); PG8_MMA(0, 1, At, B1); PG8_BAR; PG8_SCHED;
;             PG8_LDA(At, 1, 1); PG8_STAGE(PG8_SB(1, 0), b3, voffB); PG8_STAGE(PG8_SB(1, 1), b3 + hstep, voffB); PG8_STAGE(PG8_SA(1, 0), a3, voffA);
;             PG8_WAIT_V(8); PG8_WAIT_L(0); PG8_BAR; PG8_MMA(1, 0, At, B0); PG8_MMA(1, 1, At, B1); PG8_BAR; PG8_SCHED;
	s_setprio 2
	v_mfma_f32_16x16x32_bf16 v[92:95], v[128:131], v[182:185], v[92:95]
	v_mfma_f32_16x16x32_bf16 v[88:91], v[150:153], v[182:185], v[88:91]
	v_mfma_f32_16x16x32_bf16 v[84:87], v[128:131], v[190:193], v[84:87]
	v_mfma_f32_16x16x32_bf16 v[80:83], v[150:153], v[190:193], v[80:83]
	v_mfma_f32_16x16x32_bf16 v[76:79], v[128:131], v[198:201], v[76:79]
	v_mfma_f32_16x16x32_bf16 v[72:75], v[150:153], v[198:201], v[72:75]
	v_mfma_f32_16x16x32_bf16 v[60:63], v[128:131], v[206:209], v[60:63]
	v_mfma_f32_16x16x32_bf16 v[56:59], v[150:153], v[206:209], v[56:59]
	v_mfma_f32_16x16x32_bf16 v[92:95], v[132:135], v[186:189], v[92:95]
	v_mfma_f32_16x16x32_bf16 v[88:91], v[162:165], v[186:189], v[88:91]
	v_mfma_f32_16x16x32_bf16 v[84:87], v[132:135], v[194:197], v[84:87]
	v_mfma_f32_16x16x32_bf16 v[80:83], v[162:165], v[194:197], v[80:83]
	v_mfma_f32_16x16x32_bf16 v[76:79], v[132:135], v[202:205], v[76:79]
	v_mfma_f32_16x16x32_bf16 v[72:75], v[162:165], v[202:205], v[72:75]
	v_mfma_f32_16x16x32_bf16 v[60:63], v[132:135], v[210:213], v[60:63]
	v_mfma_f32_16x16x32_bf16 v[56:59], v[162:165], v[210:213], v[56:59]
	v_mfma_f32_16x16x32_bf16 v[28:31], v[166:169], v[182:185], v[28:31]
	v_mfma_f32_16x16x32_bf16 v[24:27], v[174:177], v[182:185], v[24:27]
	v_mfma_f32_16x16x32_bf16 v[20:23], v[166:169], v[190:193], v[20:23]
	v_mfma_f32_16x16x32_bf16 v[16:19], v[174:177], v[190:193], v[16:19]
	v_mfma_f32_16x16x32_bf16 v[12:15], v[166:169], v[198:201], v[12:15]
	v_mfma_f32_16x16x32_bf16 v[8:11], v[174:177], v[198:201], v[8:11]
	v_mfma_f32_16x16x32_bf16 v[4:7], v[166:169], v[206:209], v[4:7]
	v_mfma_f32_16x16x32_bf16 v[0:3], v[174:177], v[206:209], v[0:3]
	v_mfma_f32_16x16x32_bf16 v[28:31], v[170:173], v[186:189], v[28:31]
	v_mfma_f32_16x16x32_bf16 v[24:27], v[178:181], v[186:189], v[24:27]
	v_mfma_f32_16x16x32_bf16 v[20:23], v[170:173], v[194:197], v[20:23]
	v_mfma_f32_16x16x32_bf16 v[16:19], v[178:181], v[194:197], v[16:19]
	v_mfma_f32_16x16x32_bf16 v[12:15], v[170:173], v[202:205], v[12:15]
	v_mfma_f32_16x16x32_bf16 v[8:11], v[178:181], v[202:205], v[8:11]
	v_mfma_f32_16x16x32_bf16 v[4:7], v[170:173], v[210:213], v[4:7]
	v_mfma_f32_16x16x32_bf16 v[0:3], v[178:181], v[210:213], v[0:3]
	s_setprio 0
	s_add_i32 s59, s59, 2
	s_add_u32 s18, s18, 0x100
	s_addc_u32 s19, s19, 0
	s_add_u32 s57, s57, 0x100
	s_addc_u32 s58, s58, 0
	s_cmpk_gt_u32 s59, 0xfd
